# attention: V^T LDS rows 80 B with key order permuted at staging so each V^T fragment is one ds_read_b128 instead of ds_read2_b64
# speedup vs baseline: 1.0211x; 1.0211x over previous
.LBB0_111:
	s_sub_i32 s77, s70, 64
	s_lshr_b32 s20, s2, 6
	s_add_u32 s4, s30, 0x11400000
	v_writelane_b32 v251, s4, 6
	s_addc_u32 s4, s31, 0
	v_writelane_b32 v251, s4, 7
	s_add_u32 s4, s30, 0x8000000
	v_writelane_b32 v251, s4, 8
	s_addc_u32 s4, s31, 0
	v_writelane_b32 v251, s4, 9
	s_add_u32 s4, s30, 0x13400000
	v_writelane_b32 v251, s4, 10
	s_addc_u32 s4, s31, 0
	v_writelane_b32 v251, s4, 11
	s_add_u32 s4, s30, 0x2d628000
	v_writelane_b32 v251, s4, 12
	s_addc_u32 s4, s31, 0
	s_add_u32 s14, s30, 0x1f400000
	s_addc_u32 s15, s31, 0
	s_lshr_b32 s78, s2, 8
	v_writelane_b32 v251, s4, 13
	s_bfe_u32 s7, s2, 0x20006
	s_lshl_b32 s4, s78, 13
	s_lshl_b32 s57, s20, 10
	s_lshl_b32 s79, s78, 6
	v_writelane_b32 v251, s4, 14
	s_lshl_b32 s71, s7, 5
	s_lshl_b32 s4, s7, 12
	s_cmpk_lt_i32 s67, 0x400
	v_writelane_b32 v251, s4, 15
	s_cselect_b64 s[4:5], -1, 0
	v_writelane_b32 v251, s4, 16
	v_lshrrev_b32_e32 v2, 20, v0
	v_lshrrev_b32_e32 v0, 10, v0
	v_writelane_b32 v251, s5, 17
	s_ashr_i32 s4, s67, 31
	v_writelane_b32 v251, s4, 18
	s_lshr_b32 s4, s4, 29
	s_add_i32 s5, s67, s4
	s_ashr_i32 s4, s5, 3
	s_and_b32 s5, s5, -8
	s_sub_i32 s5, s67, s5
	s_lshl_b32 s6, s5, 7
	s_cmp_eq_u32 s78, 1
	s_cselect_b64 s[40:41], -1, 0
	s_cmpk_lt_u32 s2, 0x100
	s_cselect_b64 s[42:43], -1, 0
	s_cmp_eq_u32 s7, 0
	s_cselect_b64 s[8:9], -1, 0
	v_writelane_b32 v251, s8, 19
	v_or_b32_e32 v0, v0, v2
	v_cndmask_b32_e64 v196, 0, 1, s[40:41]
	v_writelane_b32 v251, s9, 20
	s_ashr_i32 s8, s70, 31
	v_writelane_b32 v251, s8, 21
	s_lshl_b32 s8, s7, 2
	s_add_i32 s8, s8, 0
	s_add_i32 s8, s8, 0x20000
	s_cmp_gt_i32 s49, -1
	v_writelane_b32 v251, s8, 22
	s_cselect_b64 s[8:9], -1, 0
	v_writelane_b32 v251, s8, 23
	v_mbcnt_lo_u32_b32 v2, -1, 0
	v_mov_b32_e32 v197, 0x358637bd
	v_writelane_b32 v251, s9, 24
	s_add_u32 s8, s30, 0x2d608200
	s_addc_u32 s9, s31, 0
	s_add_u32 s22, s30, 0x2d608400
	s_addc_u32 s23, s31, 0
	s_add_u32 s24, s30, 0x2d608500
	s_addc_u32 s25, s31, 0
	s_add_u32 s26, s30, 0x2d608600
	s_addc_u32 s27, s31, 0
	s_add_u32 s34, s30, 0x2d608700
	s_addc_u32 s35, s31, 0
	s_add_u32 s44, s30, 0x2d608800
	s_addc_u32 s45, s31, 0
	s_add_u32 s50, s30, 0x2d608900
	v_writelane_b32 v251, s8, 25
	s_addc_u32 s51, s31, 0
	v_mov_b32_e32 v198, 1
	v_writelane_b32 v251, s9, 26
	s_add_u32 s8, s30, 0x2d608a00
	s_addc_u32 s9, s31, 0
	v_writelane_b32 v251, s8, 27
	v_mov_b32_e32 v199, 0x3d2aaaab
	v_mbcnt_hi_u32_b32 v200, -1, v2
	v_writelane_b32 v251, s9, 28
	s_add_u32 s8, s30, 0x2d608b00
	s_addc_u32 s9, s31, 0
	v_writelane_b32 v251, s8, 29
	v_mov_b32_e32 v201, 0x3e0293ee
	v_mov_b32_e32 v202, 0xff800000
	v_writelane_b32 v251, s9, 30
	s_add_u32 s8, s30, 0x2d608c00
	s_addc_u32 s9, s31, 0
	v_writelane_b32 v251, s8, 31
	v_mov_b32_e32 v203, 0x41b17218
	v_mov_b32_e32 v204, 0x6000
	v_writelane_b32 v251, s9, 32
	s_add_u32 s8, s30, 0x2d608d00
	s_addc_u32 s9, s31, 0
	v_writelane_b32 v251, s8, 33
	v_mov_b64_e32 v[248:249], 0x100
	s_movk_i32 s28, 0x6000
	v_writelane_b32 v251, s9, 34
	s_add_u32 s8, s30, 0x2d608e00
	s_addc_u32 s9, s31, 0
	v_writelane_b32 v251, s8, 35
	s_mov_b32 s81, 0x800000
	s_mov_b32 s82, 0xbfb8aa3b
	v_writelane_b32 v251, s9, 36
	s_add_u32 s8, s30, 0x2d608f00
	s_addc_u32 s9, s31, 0
	v_writelane_b32 v251, s8, 37
	s_movk_i32 s66, 0x3000
	s_movk_i32 s29, 0x110
	v_writelane_b32 v251, s9, 38
	s_add_u32 s8, s30, 0x2d609000
	s_addc_u32 s9, s31, 0
	v_writelane_b32 v251, s8, 39
	s_mov_b32 s80, 0x41000000
	s_mov_b32 s65, 0x3f317217
	v_writelane_b32 v251, s9, 40
	s_add_u32 s8, s30, 0x2d609100
	s_addc_u32 s9, s31, 0
	v_writelane_b32 v251, s8, 41
	s_mov_b32 s56, 0x7f800000
	s_mov_b32 s83, 0xbe800000
	v_writelane_b32 v251, s9, 42
	s_add_u32 s8, s30, 0x2d609200
	s_addc_u32 s9, s31, 0
	v_writelane_b32 v251, s8, 43
	s_mov_b64 s[62:63], 0x80
	s_mov_b32 s68, 0x3fb8aa3b
	v_writelane_b32 v251, s9, 44
	s_add_u32 s8, s30, 0x2d609300
	s_addc_u32 s9, s31, 0
	v_writelane_b32 v251, s8, 45
	s_cmp_eq_u32 s36, 15
	s_mov_b64 s[38:39], 0x10000
	v_writelane_b32 v251, s9, 46
	s_cselect_b64 s[8:9], -1, 0
	v_writelane_b32 v251, s8, 47
	s_cmp_eq_u32 s36, 14
	s_nop 0
	v_writelane_b32 v251, s9, 48
	s_cselect_b64 s[8:9], -1, 0
	v_writelane_b32 v251, s8, 49
	s_cmp_eq_u32 s36, 13
	s_nop 0
	v_writelane_b32 v251, s9, 50
	s_cselect_b64 s[8:9], -1, 0
	v_writelane_b32 v251, s8, 51
	s_cmp_eq_u32 s36, 12
	s_nop 0
	v_writelane_b32 v251, s9, 52
	s_cselect_b64 s[8:9], -1, 0
	v_writelane_b32 v251, s8, 53
	s_cmp_eq_u32 s36, 11
	s_nop 0
	v_writelane_b32 v251, s9, 54
	s_cselect_b64 s[8:9], -1, 0
	v_writelane_b32 v251, s8, 55
	s_cmp_eq_u32 s36, 10
	s_nop 0
	v_writelane_b32 v251, s9, 56
	s_cselect_b64 s[8:9], -1, 0
	v_writelane_b32 v251, s8, 57
	s_cmp_eq_u32 s36, 9
	s_nop 0
	v_writelane_b32 v251, s9, 58
	s_cselect_b64 s[8:9], -1, 0
	v_writelane_b32 v251, s8, 59
	s_cmp_eq_u32 s36, 8
	s_nop 0
	v_writelane_b32 v251, s9, 60
	s_cselect_b64 s[8:9], -1, 0
	v_writelane_b32 v251, s8, 61
	s_cmp_eq_u32 s36, 7
	s_nop 0
	v_writelane_b32 v251, s9, 62
	s_cselect_b64 s[8:9], -1, 0
	v_writelane_b32 v251, s8, 63
	s_cmp_eq_u32 s36, 6
	s_nop 0
	v_writelane_b32 v252, s9, 0
	s_cselect_b64 s[8:9], -1, 0
	v_writelane_b32 v252, s8, 1
	s_cmp_eq_u32 s36, 5
	s_nop 0
	v_writelane_b32 v252, s9, 2
	s_cselect_b64 s[8:9], -1, 0
	v_writelane_b32 v252, s8, 3
	s_cmp_eq_u32 s36, 4
	s_nop 0
	v_writelane_b32 v252, s9, 4
	s_cselect_b64 s[8:9], -1, 0
	v_writelane_b32 v252, s8, 5
	s_cmp_eq_u32 s36, 3
	s_nop 0
	v_writelane_b32 v252, s9, 6
	s_cselect_b64 s[8:9], -1, 0
	v_writelane_b32 v252, s8, 7
	s_cmp_eq_u32 s36, 2
	s_nop 0
	v_writelane_b32 v252, s9, 8
	s_cselect_b64 s[8:9], -1, 0
	v_writelane_b32 v252, s8, 9
	s_cmp_eq_u32 s36, 1
	s_nop 0
	v_writelane_b32 v252, s9, 10
	s_cselect_b64 s[8:9], -1, 0
	v_writelane_b32 v252, s8, 11
	s_cmp_eq_u32 s36, 0
	s_nop 0
	v_writelane_b32 v252, s9, 12
	s_cselect_b64 s[8:9], -1, 0
	v_writelane_b32 v252, s8, 13
	s_nop 1
	v_writelane_b32 v252, s9, 14
	s_lshl_b32 s8, s36, 8
	s_add_u32 s8, s12, s8
	s_addc_u32 s9, s13, 0
	s_add_u32 s10, s8, 0x1400
	s_addc_u32 s11, s9, 0
	v_writelane_b32 v252, s10, 15
	s_add_u32 s8, s8, 0x2400
	s_addc_u32 s9, s9, 0
	v_writelane_b32 v252, s11, 16
	v_writelane_b32 v252, s8, 17
	s_nop 1
	v_writelane_b32 v252, s9, 18
	s_add_u32 s8, s30, 0x2d60b400
	s_addc_u32 s9, s31, 0
	v_writelane_b32 v252, s8, 19
	s_nop 1
	v_writelane_b32 v252, s9, 20
	s_add_u32 s8, s30, 0x2d60b500
	s_addc_u32 s9, s31, 0
	v_writelane_b32 v252, s8, 21
	s_nop 1
	v_writelane_b32 v252, s9, 22
	s_add_u32 s8, s30, 0x29400000
	v_writelane_b32 v252, s8, 23
	s_addc_u32 s8, s31, 0
	s_cmpk_lt_i32 s67, 0x100
	v_writelane_b32 v252, s8, 24
	s_cselect_b64 s[8:9], -1, 0
	v_writelane_b32 v252, s8, 25
	s_cmpk_eq_i32 s70, 0x100
	s_cselect_b64 s[10:11], -1, 0
	v_writelane_b32 v252, s9, 26
	s_mul_i32 s8, s20, 0x2200
	s_add_i32 s75, s8, 0
	s_lshl_b32 s7, s7, 15
	v_writelane_b32 v252, s10, 27
	s_add_i32 s75, s75, 0x12800
	s_add_i32 s76, s7, 0
	s_lshl_b32 s7, s78, 7
	v_writelane_b32 v252, s11, 28
	s_add_u32 s8, s30, 0x2d600000
	v_writelane_b32 v252, s8, 29
	s_addc_u32 s8, s31, 0
	v_writelane_b32 v252, s8, 30
	s_add_u32 s8, s30, 0x2d610000
	v_writelane_b32 v252, s8, 31
	s_addc_u32 s8, s31, 0
	v_writelane_b32 v252, s8, 32
	s_lshl_b32 s8, s20, 5
	s_and_b32 s9, s8, 0x60
	v_writelane_b32 v252, s9, 33
	s_lshr_b32 s9, s9, 3
	s_cmpk_lt_i32 s67, 0x600
	v_writelane_b32 v252, s9, 34
	s_cselect_b64 s[10:11], -1, 0
	v_writelane_b32 v252, s10, 35
	s_cmp_gt_i32 s67, 63
	s_mulk_i32 s78, 0x2200
	v_writelane_b32 v252, s11, 36
	s_cselect_b64 s[10:11], -1, 0
	v_writelane_b32 v252, s10, 37
	s_nop 1
	v_writelane_b32 v252, s11, 38
	s_sub_i32 s10, s67, 64
	s_add_u32 s9, s30, 0x23400000
	v_writelane_b32 v252, s9, 39
	s_addc_u32 s9, s31, 0
	v_writelane_b32 v252, s9, 40
	s_add_u32 s9, s30, 0x2d400000
	v_writelane_b32 v252, s9, 41
	s_addc_u32 s9, s31, 0
	v_writelane_b32 v252, s9, 42
	s_lshl_b32 s9, s10, 9
	s_add_i32 s9, s33, s9
	s_lshl_b32 s12, s77, 9
	s_add_u32 s16, s30, 0x2d60c200
	v_writelane_b32 v252, s9, 43
	s_addc_u32 s17, s31, 0
	v_writelane_b32 v252, s16, 44
	s_nop 1
	v_writelane_b32 v252, s17, 45
	s_add_u32 s16, s30, 0x2d60c400
	s_addc_u32 s17, s31, 0
	v_writelane_b32 v252, s16, 46
	s_nop 1
	v_writelane_b32 v252, s17, 47
	s_add_u32 s16, s30, 0x2d60c500
	s_addc_u32 s17, s31, 0
	v_writelane_b32 v252, s16, 48
	s_nop 1
	v_writelane_b32 v252, s17, 49
	s_add_u32 s16, s30, 0x2d60c600
	s_addc_u32 s17, s31, 0
	v_writelane_b32 v252, s16, 50
	s_nop 1
	v_writelane_b32 v252, s17, 51
	s_add_u32 s16, s30, 0x2d60c700
	s_addc_u32 s17, s31, 0
	v_writelane_b32 v252, s16, 52
	s_nop 1
	v_writelane_b32 v252, s17, 53
	s_add_u32 s16, s30, 0x2d60c800
	s_addc_u32 s17, s31, 0
	v_writelane_b32 v252, s16, 54
	s_nop 1
	v_writelane_b32 v252, s17, 55
	s_add_u32 s16, s30, 0x2d60c900
	s_addc_u32 s17, s31, 0
	v_writelane_b32 v252, s16, 56
	s_nop 1
	v_writelane_b32 v252, s17, 57
	s_add_u32 s16, s30, 0x2d60ca00
	s_addc_u32 s17, s31, 0
	v_writelane_b32 v252, s16, 58
	s_nop 1
	v_writelane_b32 v252, s17, 59
	s_add_u32 s16, s30, 0x2d60cb00
	s_addc_u32 s17, s31, 0
	v_writelane_b32 v252, s16, 60
	s_nop 1
	v_writelane_b32 v252, s17, 61
	s_add_u32 s16, s30, 0x2d60cc00
	s_addc_u32 s17, s31, 0
	v_writelane_b32 v252, s16, 62
	s_nop 1
	v_writelane_b32 v252, s17, 63
	s_add_u32 s16, s30, 0x2d60cd00
	s_addc_u32 s17, s31, 0
	v_writelane_b32 v253, s16, 0
	s_nop 1
	v_writelane_b32 v253, s17, 1
	s_add_u32 s16, s30, 0x2d60ce00
	s_addc_u32 s17, s31, 0
	v_writelane_b32 v253, s16, 2
	s_nop 1
	v_writelane_b32 v253, s17, 3
	s_add_u32 s16, s30, 0x2d60cf00
	s_addc_u32 s17, s31, 0
	v_writelane_b32 v253, s16, 4
	s_nop 1
	v_writelane_b32 v253, s17, 5
	s_add_u32 s16, s30, 0x2d60d000
	s_addc_u32 s17, s31, 0
	v_writelane_b32 v253, s16, 6
	s_nop 1
	v_writelane_b32 v253, s17, 7
	s_add_u32 s16, s30, 0x2d60d100
	s_addc_u32 s17, s31, 0
	v_writelane_b32 v253, s16, 8
	s_nop 1
	v_writelane_b32 v253, s17, 9
	s_add_u32 s16, s30, 0x2d60d200
	s_addc_u32 s17, s31, 0
	v_writelane_b32 v253, s16, 10
	s_nop 1
	v_writelane_b32 v253, s17, 11
	s_add_u32 s16, s30, 0x2d60d300
	s_addc_u32 s17, s31, 0
	v_writelane_b32 v253, s16, 12
	s_cmp_eq_u32 s3, 15
	s_nop 0
	v_writelane_b32 v253, s17, 13
	s_cselect_b64 s[16:17], -1, 0
	v_writelane_b32 v253, s16, 14
	s_cmp_eq_u32 s3, 14
	s_nop 0
	v_writelane_b32 v253, s17, 15
	s_cselect_b64 s[16:17], -1, 0
	v_writelane_b32 v253, s16, 16
	s_cmp_eq_u32 s3, 13
	s_nop 0
	v_writelane_b32 v253, s17, 17
	s_cselect_b64 s[16:17], -1, 0
	v_writelane_b32 v253, s16, 18
	s_cmp_eq_u32 s3, 12
	s_nop 0
	v_writelane_b32 v253, s17, 19
	s_cselect_b64 s[16:17], -1, 0
	v_writelane_b32 v253, s16, 20
	s_cmp_eq_u32 s3, 11
	s_nop 0
	v_writelane_b32 v253, s17, 21
	s_cselect_b64 s[16:17], -1, 0
	v_writelane_b32 v253, s16, 22
	s_cmp_eq_u32 s3, 10
	s_nop 0
	v_writelane_b32 v253, s17, 23
	s_cselect_b64 s[16:17], -1, 0
	v_writelane_b32 v253, s16, 24
	s_cmp_eq_u32 s3, 9
	s_nop 0
	v_writelane_b32 v253, s17, 25
	s_cselect_b64 s[16:17], -1, 0
	v_writelane_b32 v253, s16, 26
	s_cmp_eq_u32 s3, 8
	s_nop 0
	v_writelane_b32 v253, s17, 27
	s_cselect_b64 s[16:17], -1, 0
	v_writelane_b32 v253, s16, 28
	s_cmp_eq_u32 s3, 7
	s_nop 0
	v_writelane_b32 v253, s17, 29
	s_cselect_b64 s[16:17], -1, 0
	v_writelane_b32 v253, s16, 30
	s_cmp_eq_u32 s3, 6
	s_nop 0
	v_writelane_b32 v253, s17, 31
	s_cselect_b64 s[16:17], -1, 0
	v_writelane_b32 v253, s16, 32
	s_cmp_eq_u32 s3, 5
	s_nop 0
	v_writelane_b32 v253, s17, 33
	s_cselect_b64 s[16:17], -1, 0
	v_writelane_b32 v253, s16, 34
	s_cmp_eq_u32 s3, 4
	s_nop 0
	v_writelane_b32 v253, s17, 35
	s_cselect_b64 s[16:17], -1, 0
	v_writelane_b32 v253, s16, 36
	s_cmp_eq_u32 s3, 3
	s_nop 0
	v_writelane_b32 v253, s17, 37
	s_cselect_b64 s[16:17], -1, 0
	v_writelane_b32 v253, s16, 38
	s_cmp_eq_u32 s3, 2
	s_nop 0
	v_writelane_b32 v253, s17, 39
	s_cselect_b64 s[16:17], -1, 0
	v_writelane_b32 v253, s16, 40
	s_cmp_eq_u32 s3, 1
	s_nop 0
	v_writelane_b32 v253, s17, 41
	s_cselect_b64 s[16:17], -1, 0
	v_writelane_b32 v253, s16, 42
	s_cmp_eq_u32 s3, 0
	s_nop 0
	v_writelane_b32 v253, s17, 43
	s_cselect_b64 s[16:17], -1, 0
	s_lshl_b32 s3, s3, 8
	s_add_u32 s0, s0, s3
	v_writelane_b32 v253, s16, 44
	s_addc_u32 s1, s1, 0
	s_nop 0
	v_writelane_b32 v253, s17, 45
	s_add_u32 s16, s0, 0x1400
	s_addc_u32 s17, s1, 0
	v_writelane_b32 v253, s16, 46
	s_add_u32 s0, s0, 0x2400
	s_addc_u32 s1, s1, 0
	v_writelane_b32 v253, s17, 47
	v_writelane_b32 v253, s0, 48
	s_nop 1
	v_writelane_b32 v253, s1, 49
	s_add_u32 s0, s30, 0x2d60f400
	s_addc_u32 s1, s31, 0
	v_writelane_b32 v253, s0, 50
	s_nop 1
	v_writelane_b32 v253, s1, 51
	s_add_u32 s0, s30, 0x2d60f500
	s_addc_u32 s1, s31, 0
	v_writelane_b32 v253, s0, 52
	s_nop 1
	v_writelane_b32 v253, s1, 53
	s_add_u32 s0, s30, 0xd000000
	v_writelane_b32 v253, s0, 54
	s_addc_u32 s0, s31, 0
	s_cmpk_lt_i32 s67, 0x240
	v_writelane_b32 v253, s0, 55
	s_cselect_b64 s[0:1], -1, 0
	v_writelane_b32 v253, s0, 56
	s_nop 1
	v_writelane_b32 v253, s1, 57
	s_lshl_b32 s0, s10, 2
	s_and_b32 s0, s0, 0xffffff00
	s_ashr_i32 s1, s0, 31
	s_lshl_b64 s[0:1], s[0:1], 1
	v_writelane_b32 v253, s0, 58
	s_nop 1
	v_writelane_b32 v253, s1, 59
	v_writelane_b32 v253, s10, 60
	s_and_b32 s1, s67, 31
	v_writelane_b32 v253, s1, 61
	s_lshl_b32 s1, s1, 20
	s_ashr_i32 s0, s10, 5
	v_writelane_b32 v253, s1, 62
	v_writelane_b32 v253, s0, 63
	s_ashr_i32 s0, s0, 31
	s_cmpk_lt_i32 s67, 0x840
	v_writelane_b32 v254, s0, 0
	s_cselect_b64 s[0:1], -1, 0
	v_writelane_b32 v254, s0, 1
	s_nop 1
	v_writelane_b32 v254, s1, 2
	s_lshl_b32 s0, s77, 1
	v_writelane_b32 v254, s0, 3
	s_add_u32 s0, s30, 0xc000000
	v_writelane_b32 v254, s0, 4
	s_addc_u32 s0, s31, 0
	v_writelane_b32 v254, s0, 5
	s_add_u32 s0, s30, 0x6000000
	v_writelane_b32 v254, s0, 6
	s_addc_u32 s0, s31, 0
	s_cmpk_lt_i32 s67, 0x440
	v_writelane_b32 v254, s0, 7
	s_cselect_b64 s[0:1], -1, 0
	v_writelane_b32 v254, s0, 8
	s_cmpk_lt_i32 s67, 0xc40
	s_nop 0
	v_writelane_b32 v254, s1, 9
	s_cselect_b64 s[0:1], -1, 0
	v_writelane_b32 v254, s0, 10
	s_lshl_b32 s3, s67, 7
	s_and_b32 s13, s3, 0xfffff800
	v_writelane_b32 v254, s1, 11
	s_lshl_b32 s0, s20, 3
	s_add_i32 s0, s0, s13
	s_ashr_i32 s1, s0, 31
	s_lshl_b64 s[10:11], s[0:1], 13
	v_writelane_b32 v254, s14, 12
	s_add_u32 s1, s14, s10
	v_writelane_b32 v254, s15, 13
	s_addc_u32 s9, s15, s11
	s_and_b32 s3, s3, 0x780
	v_writelane_b32 v254, s3, 14
	s_lshl_b32 s3, s3, 2
	s_add_u32 s1, s1, s3
	v_writelane_b32 v254, s1, 15
	s_addc_u32 s1, s9, 0
	v_writelane_b32 v254, s1, 16
	s_lshl_b32 s1, s20, 9
	s_add_i32 s1, s1, 0
	s_mov_b32 s15, s12
	s_add_i32 s18, s1, 0x20a00
	s_lshl_b32 s1, s20, 4
	s_and_b32 s12, s2, 64
	s_cmp_lt_u32 s2, 64
	v_writelane_b32 v254, s1, 17
	s_cselect_b64 s[10:11], -1, 0
	v_writelane_b32 v254, s10, 18
	s_cmp_gt_u32 s2, 63
	s_mov_b32 s14, 0x42e60000
	v_writelane_b32 v254, s11, 19
	s_cselect_b64 s[10:11], -1, 0
	v_writelane_b32 v254, s10, 20
	s_cmpk_lt_u32 s2, 0x280
	s_nop 0
	v_writelane_b32 v254, s11, 21
	s_cselect_b64 s[10:11], -1, 0
	s_lshr_b32 s1, s2, 7
	s_lshl_b32 s3, s1, 4
	s_lshl_b32 s1, s1, 6
	s_add_i32 s1, s1, 0
	v_writelane_b32 v254, s10, 22
	s_add_i32 s9, s1, 0x21a00
	s_lshl_b32 s1, s12, 2
	v_writelane_b32 v254, s11, 23
	s_add_i32 s1, s9, s1
	v_writelane_b32 v254, s9, 24
	s_cmpk_gt_u32 s2, 0x7f
	v_writelane_b32 v254, s1, 25
	s_cselect_b64 s[10:11], -1, 0
	v_writelane_b32 v254, s10, 26
	s_cmpk_gt_u32 s2, 0xbf
	s_movk_i32 s1, 0x3ff
	v_writelane_b32 v254, s11, 27
	s_cselect_b64 s[10:11], -1, 0
	v_writelane_b32 v254, s10, 28
	s_cmpk_gt_u32 s2, 0xff
	v_and_or_b32 v0, v0, s1, v1
	v_writelane_b32 v254, s11, 29
	s_cselect_b64 s[10:11], -1, 0
	v_writelane_b32 v254, s10, 30
	s_cmpk_gt_u32 s2, 0x13f
	s_mul_hi_i32 s1, s0, 0x6000
	v_writelane_b32 v254, s11, 31
	s_cselect_b64 s[10:11], -1, 0
	v_writelane_b32 v254, s10, 32
	s_cmpk_gt_u32 s2, 0x17f
	s_mulk_i32 s0, 0x6000
	v_writelane_b32 v254, s11, 33
	s_cselect_b64 s[10:11], -1, 0
	v_writelane_b32 v254, s10, 34
	s_cmpk_gt_u32 s2, 0x1bf
	v_mov_b32_e32 v1, 0
	v_writelane_b32 v254, s11, 35
	s_cselect_b64 s[10:11], -1, 0
	v_writelane_b32 v254, s10, 36
	s_cmpk_gt_u32 s2, 0x1ff
	s_mul_i32 s2, s5, 33
	v_writelane_b32 v254, s11, 37
	v_writelane_b32 v254, s1, 38
	v_writelane_b32 v254, s0, 39
	s_cselect_b64 s[10:11], -1, 0
	v_writelane_b32 v254, s10, 40
	s_mul_i32 s0, s20, 0x900
	s_add_i32 s0, s0, 0
	v_writelane_b32 v254, s11, 41
	v_writelane_b32 v254, s13, 42
	s_add_i32 s19, s0, 0x11400
	v_writelane_b32 v254, s3, 43
	s_add_i32 s0, s3, s13
	v_writelane_b32 v254, s0, 44
	s_add_u32 s0, s30, 0xd400000
	v_writelane_b32 v254, s0, 45
	s_addc_u32 s0, s31, 0
	v_writelane_b32 v254, s0, 46
	s_lshl_b32 s0, s5, 5
	s_cmp_lt_i32 s5, 0
	s_mul_i32 s1, s5, 0x81
	s_cselect_b32 s1, s1, s6
	s_cselect_b32 s0, s2, s0
	s_movk_i32 s2, 0xc1
	s_cselect_b32 s2, s2, 0xc0
	s_add_i32 s1, s1, s4
	s_ashr_i32 s3, s1, 31
	s_lshr_b32 s3, s3, 24
	s_add_i32 s3, s1, s3
	s_and_b32 s6, s3, 0xff00
	s_sub_i32 s1, s1, s6
	s_sext_i32_i16 s6, s1
	s_bfe_u32 s6, s6, 0x3001c
	s_mul_i32 s2, s5, s2
	s_add_i32 s6, s1, s6
	s_add_i32 s2, s2, s4
	s_and_b32 s9, s6, 0xfff8
	s_mul_hi_i32 s5, s2, 0x2aaaaaab
	s_sub_i32 s1, s1, s9
	s_lshr_b32 s9, s5, 31
	s_ashr_i32 s5, s5, 6
	s_add_i32 s5, s5, s9
	s_mul_i32 s9, s5, 0x180
	s_sub_i32 s2, s2, s9
	s_add_i32 s0, s0, s4
	s_bfe_u32 s9, s2, 0x3001c
	s_ashr_i32 s4, s0, 31
	s_add_i32 s9, s2, s9
	s_lshr_b32 s4, s4, 26
	s_and_b32 s10, s9, 0xfff8
	s_add_i32 s4, s0, s4
	s_sub_i32 s2, s2, s10
	s_and_b32 s10, s4, 0xffc0
	s_sub_i32 s0, s0, s10
	s_bfe_i32 s10, s0, 0x80000
	s_bfe_u32 s10, s10, 0x3000c
	s_mov_b32 s13, s37
	s_ashr_i32 s3, s3, 8
	s_add_i32 s10, s0, s10
	v_writelane_b32 v254, s12, 47
	s_lshl_b32 s3, s3, 3
	s_sext_i32_i16 s1, s1
	s_and_b32 s11, s10, 0xf8
	v_writelane_b32 v254, s13, 48
	s_add_i32 s12, s3, s1
	s_lshl_b32 s1, s5, 3
	s_sext_i32_i16 s2, s2
	s_sub_i32 s0, s0, s11
	s_add_i32 s16, s1, s2
	s_ashr_i32 s1, s4, 6
	s_sext_i32_i16 s6, s6
	s_lshl_b32 s1, s1, 3
	s_sext_i32_i8 s0, s0
	s_add_i32 s4, s1, s0
	s_ashr_i32 s0, s6, 3
	v_writelane_b32 v254, s0, 49
	s_lshr_b32 s0, s6, 3
	s_bfe_i64 s[0:1], s[0:1], 0x100000
	s_lshl_b64 s[0:1], s[0:1], 20
	s_sext_i32_i16 s3, s9
	v_writelane_b32 v254, s0, 50
	s_bfe_i32 s2, s10, 0x80000
	s_ashr_i32 s5, s4, 31
	v_writelane_b32 v254, s1, 51
	s_ashr_i32 s0, s3, 3
	v_writelane_b32 v254, s0, 52
	s_lshr_b32 s0, s3, 3
	s_bfe_i64 s[0:1], s[0:1], 0x100000
	s_lshl_b64 s[0:1], s[0:1], 20
	v_writelane_b32 v254, s0, 53
	s_sext_i32_i16 s2, s2
	s_ashr_i32 s13, s12, 31
	v_writelane_b32 v254, s1, 54
	v_writelane_b32 v254, s4, 55
	s_ashr_i32 s0, s2, 3
	s_ashr_i32 s17, s16, 31
	v_writelane_b32 v254, s5, 56
	v_writelane_b32 v254, s0, 57
	s_lshr_b32 s0, s2, 3
	s_bfe_i64 s[0:1], s[0:1], 0x100000
	v_writelane_b32 v254, s0, 58
	s_nop 1
	v_writelane_b32 v254, s1, 59
	s_lshl_b32 s0, s70, 12
	s_add_i32 s0, s0, 0xfffc0000
	v_writelane_b32 v254, s0, 60
	s_mov_b32 s0, s12
	v_writelane_b32 v254, s0, 61
	s_nop 1
	v_writelane_b32 v254, s1, 62
	s_lshl_b64 s[0:1], s[12:13], 20
	v_writelane_b32 v254, s0, 63
	s_movk_i32 s13, 0x5000
	s_nop 0
	v_writelane_b32 v255, s1, 0
	s_mov_b32 s0, s16
	v_writelane_b32 v255, s0, 1
	s_nop 1
	v_writelane_b32 v255, s1, 2
	s_lshl_b64 s[0:1], s[16:17], 20
	v_writelane_b32 v255, s0, 3
	s_nop 1
	v_writelane_b32 v255, s1, 4
	s_add_u32 s0, s30, 0x2540f000
	v_writelane_b32 v255, s0, 5
	s_addc_u32 s0, s31, 0
	v_writelane_b32 v255, s0, 6
	s_lshl_b32 s0, s70, 11
	s_add_i32 s0, s0, 0xfffe0000
	v_writelane_b32 v255, s0, 7
	s_lshl_b32 s0, s20, 8
	s_add_i32 s0, s0, 0
	s_add_i32 s0, s0, 0x15c00
	v_writelane_b32 v255, s0, 8
	s_add_i32 s0, s8, 0
	s_add_i32 s0, s0, 0x15c00
	v_writelane_b32 v255, s0, 9
	s_mul_i32 s0, s20, 0x1100
	s_add_i32 s0, s0, 0
	s_add_i32 s0, s0, 0x8800
	v_writelane_b32 v255, s0, 10
	s_lshl_b32 s0, s7, 1
	v_writelane_b32 v255, s0, 11
	s_add_i32 s0, s33, 0xfffffe00
	v_writelane_b32 v255, s0, 12
	s_add_i32 s0, 0, 0x23ff0
	v_writelane_b32 v255, s0, 13
	s_add_i32 s0, 0, 0x23ff4
	v_writelane_b32 v255, s0, 14
	s_add_i32 s0, 0, 0x23ff8
	v_writelane_b32 v255, s0, 15
	s_add_i32 s0, 0, 0x23ffc
	v_writelane_b32 v255, s0, 16
	v_cmp_eq_u32_e64 s[0:1], 0, v0
	s_nop 1
	v_writelane_b32 v255, s0, 17
	s_nop 1
	v_writelane_b32 v255, s1, 18
	s_load_dwordx2 s[0:1], s[96:97], 0xa0
	s_waitcnt lgkmcnt(0)
	v_writelane_b32 v255, s0, 19
	s_nop 1
	v_writelane_b32 v255, s1, 20
	v_writelane_b32 v255, s67, 21
	v_writelane_b32 v255, s96, 22
	s_mov_b32 s0, s37
	s_nop 0
	v_writelane_b32 v255, s97, 23
	v_writelane_b32 v255, s70, 24
	v_writelane_b32 v255, s77, 25
	v_writelane_b32 v255, s20, 26
	v_writelane_b32 v255, s79, 27
	v_writelane_b32 v255, s22, 28
	s_nop 1
	v_writelane_b32 v255, s23, 29
	v_writelane_b32 v255, s24, 30
	s_nop 1
	v_writelane_b32 v255, s25, 31
	v_writelane_b32 v255, s26, 32
	s_nop 1
	v_writelane_b32 v255, s27, 33
	v_writelane_b32 v255, s34, 34
	s_nop 1
	v_writelane_b32 v255, s35, 35
	v_writelane_b32 v255, s44, 36
	s_nop 1
	v_writelane_b32 v255, s45, 37
	v_writelane_b32 v255, s50, 38
	s_nop 1
	v_writelane_b32 v255, s51, 39
	v_writelane_b32 v255, s15, 40
	v_writelane_b32 v255, s18, 41
	v_writelane_b32 v255, s19, 42
	s_branch .LBB0_114

.LBB0_301:
	s_cmp_ge_i32 s2, s48
	s_cselect_b64 s[0:1], -1, 0
	s_cmp_lt_i32 s2, s49
	s_cselect_b64 s[2:3], -1, 0
	s_and_b64 s[0:1], s[0:1], s[2:3]
	s_mov_b64 s[52:53], 0
	s_andn2_b64 vcc, exec, s[0:1]
	s_mov_b64 s[16:17], 0
	s_cbranch_vccnz .LBB0_392
	v_writelane_b32 v255, s84, 50
	v_readlane_b32 s4, v252, 25
	v_readlane_b32 s5, v252, 26
	v_writelane_b32 v255, s85, 51
	v_writelane_b32 v255, s72, 52
	s_mov_b32 s85, s37
	s_mov_b32 s84, s37
	v_writelane_b32 v255, s73, 53
	v_writelane_b32 v255, s47, 54
	s_mov_b32 s1, s37
	s_mov_b32 s0, s37
	s_mov_b32 s2, s37
	s_andn2_b64 vcc, exec, s[4:5]
	v_mbcnt_lo_u32_b32 v192, -1, 0
	v_mbcnt_hi_u32_b32 v192, -1, v192
	s_cbranch_vccnz .LBB0_325
	v_readlane_b32 s4, v255, 52
	s_mov_b32 s6, s4
	v_readlane_b32 s5, v255, 53
	v_writelane_b32 v255, s6, 52
	s_mov_b32 s5, s37
	s_lshl_b32 s36, s4, 8
	v_writelane_b32 v255, s7, 53
	s_lshl_b64 s[4:5], s[4:5], 2
	v_readlane_b32 s8, v255, 22
	v_readlane_b32 s9, v255, 23
	s_add_u32 s6, s8, s4
	s_addc_u32 s7, s9, s5
	s_ashr_i32 s67, s85, 31
	v_readlane_b32 s3, v251, 10
	s_add_u32 s52, s3, s85
	v_readlane_b32 s3, v251, 11
	s_addc_u32 s53, s3, s67
	s_ashr_i32 s69, s84, 31
	v_readlane_b32 s3, v254, 12
	s_add_u32 s3, s3, s84
	v_mov_b32_e32 v0, 0x2d604000
	v_writelane_b32 v255, s3, 55
	v_readlane_b32 s3, v254, 13
	s_addc_u32 s3, s3, s69
	s_nop 0
	v_writelane_b32 v255, s3, 56
	s_ashr_i32 s3, s1, 31
	s_add_u32 s1, s30, s1
	s_addc_u32 s3, s31, s3
	s_add_u32 s4, s1, s4
	s_addc_u32 s5, s3, s5
	global_load_dword v193, v0, s[4:5]
	s_ashr_i32 s1, s0, 31
	s_lshl_b64 s[0:1], s[0:1], 3
	s_add_u32 s0, s8, s0
	s_addc_u32 s1, s9, s1
	s_load_dwordx2 s[0:1], s[0:1], 0x90
	s_nop 0
	s_load_dword s3, s[6:7], 0xf0
	s_lshl_b64 s[4:5], s[36:37], 2
	s_waitcnt lgkmcnt(0)
	s_add_u32 s46, s0, s4
	s_addc_u32 s47, s1, s5
	v_lshlrev_b32_e32 v2, 4, v192
	global_load_dwordx4 v[4:7], v2, s[46:47]
	v_add_u32_e32 v2, 0x23800, v2
	s_waitcnt vmcnt(0)
	ds_write_b128 v2, v[4:7]
	s_ashr_i32 s0, s2, 31
	v_readlane_b32 s1, v252, 23
	s_add_u32 s74, s1, s2
	v_readlane_b32 s1, v252, 24
	s_addc_u32 s72, s1, s0
	v_readlane_b32 s0, v255, 11
	s_add_u32 s64, s52, s0
	v_sub_f32_e64 v194, 1.0, s3
	s_addc_u32 s3, s53, 0
	v_readlane_b32 s2, v255, 21
	s_branch .LBB0_305

.LBB0_307:
	s_xor_b64 s[86:87], s[4:5], -1
	s_and_b64 s[4:5], s[4:5], exec
	s_cselect_b32 s4, s48, s70
	s_lshl_b32 s5, s4, 7
	v_mov_b32_e32 v206, v192
	s_or_b32 s5, s5, s71
	s_or_b32 s35, s5, s34
	s_waitcnt vmcnt(0)
	v_ashrrev_i32_e32 v4, 1, v206
	v_add_u32_e32 v2, s35, v4
	v_ashrrev_i32_e32 v3, 31, v2
	v_lshlrev_b64 v[2:3], 14, v[2:3]
	v_lshlrev_b32_e32 v0, 7, v206
	v_lshl_add_u64 v[2:3], s[26:27], 0, v[2:3]
	v_and_b32_e32 v0, 0x80, v0
	v_lshl_add_u64 v[30:31], v[2:3], 0, v[0:1]
	v_mul_lo_u32 v2, v4, s29
	v_add_u32_e32 v34, s33, v206
	v_and_b32_e32 v56, 15, v206
	v_and_b32_e32 v58, 3, v206
	v_add3_u32 v54, s75, v2, v0
	v_ashrrev_i32_e32 v55, 4, v34
	v_lshlrev_b32_e32 v0, 3, v56
	v_ashrrev_i32_e32 v57, 2, v34
	v_lshlrev_b32_e32 v34, 3, v58
	v_lshl_or_b32 v0, v55, 13, v0
	v_lshl_or_b32 v42, v57, 11, v34
	v_mov_b32_e32 v43, v1
	v_lshlrev_b64 v[50:51], 1, v[0:1]
	v_lshlrev_b64 v[52:53], 1, v[42:43]
	v_lshl_add_u64 v[38:39], s[44:45], 0, v[50:51]
	v_lshl_add_u64 v[42:43], s[0:1], 0, v[52:53]
	v_lshl_add_u64 v[46:47], s[50:51], 0, v[52:53]
	global_load_dwordx4 v[2:5], v[30:31], off offset:48
	global_load_dwordx4 v[6:9], v[30:31], off offset:32
	global_load_dwordx4 v[10:13], v[30:31], off offset:16
	global_load_dwordx4 v[14:17], v[30:31], off
	global_load_dwordx4 v[18:21], v[30:31], off offset:112
	global_load_dwordx4 v[22:25], v[30:31], off offset:96
	global_load_dwordx4 v[26:29], v[30:31], off offset:80
	s_nop 0
	global_load_dwordx4 v[30:33], v[30:31], off offset:64
	s_nop 0
	global_load_dwordx4 v[34:37], v[38:39], off
	s_nop 0
	global_load_dwordx4 v[38:41], v[38:39], off offset:256
	s_nop 0
	global_load_dwordx4 v[42:45], v[42:43], off
	s_nop 0
	global_load_dwordx4 v[46:49], v[46:47], off
	s_lshl_b32 s28, s4, 2
	s_movk_i32 s4, 0x50
	v_mul_lo_u32 v57, v57, s4
	v_mov_b32_e32 v0, s75
	v_and_b32_e32 v205, 31, v206
	v_ashrrev_i32_e32 v195, 5, v206
	v_mul_lo_u32 v55, v55, s29
	v_and_b32_e32 v214, 2, v58
	v_lshl_add_u32 v214, v214, 4, v57
	v_and_b32_e32 v58, 1, v58
	v_lshl_add_u32 v214, v58, 3, v214
	v_mad_u32_u24 v210, v205, s29, v0
	v_lshlrev_b32_e32 v0, 2, v195
	v_lshl_add_u32 v213, v56, 4, v55
	v_add_u32_e32 v56, 0, v214
	v_add_u32_e32 v55, 0, v213
	v_add_u32_e32 v57, 0x4400, v56
	v_add_u32_e32 v56, 0x6c00, v56
	v_cmp_gt_i32_e64 s[90:91], v0, v205
	v_cmp_lt_i32_e64 s[88:89], v0, v205
	v_or_b32_e32 v59, 2, v0
	v_or_b32_e32 v60, 3, v0
	v_add_u32_e32 v61, 8, v0
	v_add_u32_e32 v62, 9, v0
	v_add_u32_e32 v63, 10, v0
	v_add_u32_e32 v64, 11, v0
	v_add_u32_e32 v65, 16, v0
	s_lshr_b32 s49, s5, 5
	v_cmp_gt_i32_e64 s[92:93], v59, v205
	v_cmp_gt_i32_e64 s[94:95], v60, v205
	v_cmp_gt_i32_e64 s[96:97], v61, v205
	v_cmp_gt_i32_e64 s[4:5], v62, v205
	v_cmp_gt_i32_e64 s[6:7], v63, v205
	v_cmp_gt_i32_e64 s[8:9], v64, v205
	v_cmp_gt_i32_e64 s[10:11], v65, v205
	v_lshl_add_u64 v[188:189], s[60:61], 0, v[52:53]
	v_lshl_add_u64 v[190:191], s[54:55], 0, v[50:51]
	v_mul_u32_u24_e32 v211, 0x110, v205
	v_lshlrev_b32_e32 v209, 4, v195
	v_mul_u32_u24_e32 v212, 0x50, v205
	v_lshlrev_b32_e32 v208, 4, v195
	s_or_b32 s79, s28, 3
	s_mov_b32 s77, 0
	v_mov_b32_e32 v207, 0
	v_mov_b32_e32 v215, 0xff800000
	s_waitcnt vmcnt(0)
	ds_write_b128 v54, v[14:17]
	ds_write_b128 v54, v[10:13] offset:16
	ds_write_b128 v54, v[6:9] offset:32
	ds_write_b128 v54, v[2:5] offset:48
	ds_write_b128 v54, v[30:33] offset:64
	ds_write_b128 v54, v[26:29] offset:80
	ds_write_b128 v54, v[22:25] offset:96
	ds_write_b128 v54, v[18:21] offset:112
	ds_write_b128 v55, v[34:37]
	ds_write_b128 v55, v[38:41] offset:8704
	ds_write2_b64 v57, v[42:43], v[44:45] offset1:2
	ds_write2_b64 v56, v[46:47], v[48:49] offset1:2
	v_add_u32_e32 v2, 17, v0
	v_cmp_gt_i32_e64 s[12:13], v2, v205
	v_add_u32_e32 v2, 18, v0
	v_cmp_gt_i32_e64 s[14:15], v2, v205
	v_add_u32_e32 v2, 19, v0
	v_cmp_gt_i32_e64 s[16:17], v2, v205
	v_add_u32_e32 v2, 24, v0
	v_cmp_gt_i32_e64 s[18:19], v2, v205
	v_add_u32_e32 v2, 25, v0
	v_cmp_gt_i32_e64 s[20:21], v2, v205
	v_add_u32_e32 v2, 26, v0
	v_add_u32_e32 v0, 27, v0
	v_mov_b32_e32 v14, v1
	v_mov_b32_e32 v15, v1
	v_cmp_gt_i32_e64 s[22:23], v2, v205
	v_cmp_gt_i32_e64 s[24:25], v0, v205
	v_mov_b32_e32 v0, v1
	v_mov_b32_e32 v2, v1
	v_mov_b32_e32 v3, v1
	v_mov_b32_e32 v4, v1
	v_mov_b32_e32 v5, v1
	v_mov_b32_e32 v6, v1
	v_mov_b32_e32 v7, v1
	v_mov_b32_e32 v8, v1
	v_mov_b32_e32 v9, v1
	v_mov_b32_e32 v10, v1
	v_mov_b32_e32 v11, v1
	v_mov_b32_e32 v12, v1
	v_mov_b32_e32 v13, v1
	v_mov_b64_e32 v[30:31], v[14:15]
	v_mov_b64_e32 v[46:47], v[14:15]
	v_mov_b64_e32 v[62:63], v[14:15]
	v_mov_b64_e32 v[78:79], v[14:15]
	v_mov_b64_e32 v[94:95], v[14:15]
	v_mov_b64_e32 v[110:111], v[14:15]
	v_mov_b64_e32 v[126:127], v[14:15]
	v_mov_b64_e32 v[142:143], v[14:15]
	v_mov_b64_e32 v[28:29], v[12:13]
	v_mov_b64_e32 v[26:27], v[10:11]
	v_mov_b64_e32 v[24:25], v[8:9]
	v_mov_b64_e32 v[22:23], v[6:7]
	v_mov_b64_e32 v[20:21], v[4:5]
	v_mov_b64_e32 v[18:19], v[2:3]
	v_mov_b64_e32 v[16:17], v[0:1]
	v_mov_b64_e32 v[44:45], v[12:13]
	v_mov_b64_e32 v[42:43], v[10:11]
	v_mov_b64_e32 v[40:41], v[8:9]
	v_mov_b64_e32 v[38:39], v[6:7]
	v_mov_b64_e32 v[36:37], v[4:5]
	v_mov_b64_e32 v[34:35], v[2:3]
	v_mov_b64_e32 v[32:33], v[0:1]
	v_mov_b64_e32 v[60:61], v[12:13]
	v_mov_b64_e32 v[58:59], v[10:11]
	v_mov_b64_e32 v[56:57], v[8:9]
	v_mov_b64_e32 v[54:55], v[6:7]
	v_mov_b64_e32 v[52:53], v[4:5]
	v_mov_b64_e32 v[50:51], v[2:3]
	v_mov_b64_e32 v[48:49], v[0:1]
	v_mov_b64_e32 v[76:77], v[12:13]
	v_mov_b64_e32 v[74:75], v[10:11]
	v_mov_b64_e32 v[72:73], v[8:9]
	v_mov_b64_e32 v[70:71], v[6:7]
	v_mov_b64_e32 v[68:69], v[4:5]
	v_mov_b64_e32 v[66:67], v[2:3]
	v_mov_b64_e32 v[64:65], v[0:1]
	v_mov_b64_e32 v[92:93], v[12:13]
	v_mov_b64_e32 v[90:91], v[10:11]
	v_mov_b64_e32 v[88:89], v[8:9]
	v_mov_b64_e32 v[86:87], v[6:7]
	v_mov_b64_e32 v[84:85], v[4:5]
	v_mov_b64_e32 v[82:83], v[2:3]
	v_mov_b64_e32 v[80:81], v[0:1]
	v_mov_b64_e32 v[108:109], v[12:13]
	v_mov_b64_e32 v[106:107], v[10:11]
	v_mov_b64_e32 v[104:105], v[8:9]
	v_mov_b64_e32 v[102:103], v[6:7]
	v_mov_b64_e32 v[100:101], v[4:5]
	v_mov_b64_e32 v[98:99], v[2:3]
	v_mov_b64_e32 v[96:97], v[0:1]
	v_mov_b64_e32 v[124:125], v[12:13]
	v_mov_b64_e32 v[122:123], v[10:11]
	v_mov_b64_e32 v[120:121], v[8:9]
	v_mov_b64_e32 v[118:119], v[6:7]
	v_mov_b64_e32 v[116:117], v[4:5]
	v_mov_b64_e32 v[114:115], v[2:3]
	v_mov_b64_e32 v[112:113], v[0:1]
	v_mov_b64_e32 v[140:141], v[12:13]
	v_mov_b64_e32 v[138:139], v[10:11]
	v_mov_b64_e32 v[136:137], v[8:9]
	v_mov_b64_e32 v[134:135], v[6:7]
	v_mov_b64_e32 v[132:133], v[4:5]
	v_mov_b64_e32 v[130:131], v[2:3]
	v_mov_b64_e32 v[128:129], v[0:1]
	s_waitcnt lgkmcnt(0)
	s_barrier
	s_branch .LBB0_310
.LBB0_308:
	v_sub_f32_e32 v0, v160, v215
	v_exp_f32_e32 v0, v0
	v_sub_f32_e32 v160, v161, v215
	v_exp_f32_e32 v160, v160
	v_sub_f32_e32 v161, v162, v215
	v_exp_f32_e32 v161, v161
	v_sub_f32_e32 v162, v163, v215
	v_exp_f32_e32 v162, v162
	v_sub_f32_e32 v164, v164, v215
	v_add_f32_e32 v163, v207, v0
	v_exp_f32_e32 v164, v164
	v_add_f32_e32 v163, v160, v163
	v_add_f32_e32 v163, v161, v163
	v_sub_f32_e32 v165, v165, v215
	v_add_f32_e32 v163, v162, v163
	v_exp_f32_e32 v165, v165
	v_sub_f32_e32 v166, v166, v215
	v_exp_f32_e32 v166, v166
	v_sub_f32_e32 v167, v167, v215
	v_add_f32_e32 v163, v164, v163
	v_cvt_pk_bf16_f32 v160, v0, v160
	v_cvt_pk_bf16_f32 v161, v161, v162
	v_cvt_pk_bf16_f32 v162, v164, v165
	v_sub_f32_e32 v164, v169, v215
	v_exp_f32_e32 v167, v167
	v_sub_f32_e32 v0, v168, v215
	v_exp_f32_e32 v168, v164
	v_sub_f32_e32 v164, v170, v215
	v_exp_f32_e32 v169, v164
	v_sub_f32_e32 v164, v171, v215
	v_add_f32_e32 v163, v165, v163
	v_exp_f32_e32 v170, v164
	v_sub_f32_e32 v164, v172, v215
	v_add_f32_e32 v163, v166, v163
	v_exp_f32_e32 v171, v164
	v_sub_f32_e32 v164, v173, v215
	v_sub_f32_e32 v14, v14, v215
	v_sub_f32_e32 v15, v15, v215
	v_add_f32_e32 v175, v167, v163
	v_cvt_pk_bf16_f32 v163, v166, v167
	v_exp_f32_e32 v0, v0
	v_exp_f32_e32 v172, v164
	v_exp_f32_e32 v14, v14
	v_exp_f32_e32 v15, v15
	v_cvt_pk_bf16_f32 v164, v0, v168
	v_cvt_pk_bf16_f32 v165, v169, v170
	v_cvt_pk_bf16_f32 v166, v171, v172
	v_cvt_pk_bf16_f32 v167, v14, v15
	s_waitcnt lgkmcnt(3)
	v_mfma_f32_32x32x16_bf16 v[128:143], v[148:151], v[160:163], v[128:143]
	s_waitcnt lgkmcnt(1)
	v_mfma_f32_32x32x16_bf16 v[112:127], v[156:159], v[160:163], v[112:127]
	v_add_u32_e32 v156, 0x5800, v174
	v_mfma_f32_32x32x16_bf16 v[128:143], v[144:147], v[164:167], v[128:143]
	ds_read_b128 v[144:147], v174 offset:25120
	s_waitcnt lgkmcnt(1)
	v_mfma_f32_32x32x16_bf16 v[112:127], v[152:155], v[164:167], v[112:127]
	v_add_u32_e32 v152, 0x5000, v174
	ds_read_b128 v[148:151], v174 offset:22528
	ds_read_b128 v[152:155], v174 offset:22560
	ds_read_b128 v[156:159], v174 offset:25088
	s_waitcnt lgkmcnt(2)
	v_mfma_f32_32x32x16_bf16 v[96:111], v[148:151], v[160:163], v[96:111]
	s_waitcnt lgkmcnt(0)
	v_mfma_f32_32x32x16_bf16 v[80:95], v[156:159], v[160:163], v[80:95]
	v_subrev_u32_e32 v250, s73, v213
	s_waitcnt vmcnt(2)
	ds_write_b128 v250, v[2:5] offset:37888
	ds_write_b128 v250, v[6:9] offset:46592
	v_add_u32_e32 v156, 0x7000, v174
	v_mfma_f32_32x32x16_bf16 v[96:111], v[152:155], v[164:167], v[96:111]
	v_add_u32_e32 v152, 0x6800, v174
	v_mfma_f32_32x32x16_bf16 v[80:95], v[144:147], v[164:167], v[80:95]
	ds_read_b128 v[144:147], v174 offset:30240
	ds_read_b128 v[148:151], v174 offset:27648
	ds_read_b128 v[152:155], v174 offset:27680
	ds_read_b128 v[156:159], v174 offset:30208
	s_waitcnt lgkmcnt(2)
	v_mfma_f32_32x32x16_bf16 v[64:79], v[148:151], v[160:163], v[64:79]
	s_waitcnt lgkmcnt(0)
	v_mfma_f32_32x32x16_bf16 v[48:63], v[156:159], v[160:163], v[48:63]
	v_subrev_u32_e32 v250, s73, v214
	v_add_u32_e32 v2, 0xd800, v250
	v_add_u32_e32 v250, 0x10000, v250
	s_waitcnt vmcnt(0)
	ds_write2_b64 v2, v[10:11], v[12:13] offset1:2
	ds_write2_b64 v250, v[176:177], v[178:179] offset1:2
	v_add_u32_e32 v156, 0x8000, v174
	v_mfma_f32_32x32x16_bf16 v[64:79], v[152:155], v[164:167], v[64:79]
	v_add_u32_e32 v152, 0x7800, v174
	v_mfma_f32_32x32x16_bf16 v[48:63], v[144:147], v[164:167], v[48:63]
	ds_read_b128 v[144:147], v174 offset:35360
	ds_read_b128 v[148:151], v174 offset:32768
	ds_read_b128 v[152:155], v174 offset:32800
	ds_read_b128 v[156:159], v174 offset:35328
	s_waitcnt lgkmcnt(2)
	v_mfma_f32_32x32x16_bf16 v[32:47], v[148:151], v[160:163], v[32:47]
	s_waitcnt lgkmcnt(0)
	v_mfma_f32_32x32x16_bf16 v[16:31], v[156:159], v[160:163], v[16:31]
	v_mfma_f32_32x32x16_bf16 v[32:47], v[152:155], v[164:167], v[32:47]
	v_mfma_f32_32x32x16_bf16 v[16:31], v[144:147], v[164:167], v[16:31]
	v_add_f32_e32 v0, v0, v175
	v_add_f32_e32 v0, v168, v0
	v_add_f32_e32 v0, v169, v0
	v_add_f32_e32 v0, v170, v0
	v_add_f32_e32 v0, v171, v0
	v_add_f32_e32 v0, v172, v0
	v_add_f32_e32 v0, v14, v0
	v_add_f32_e32 v207, v15, v0
	s_add_i32 s77, s77, 1
	v_lshl_add_u64 v[188:189], v[188:189], 0, 64
	s_mov_b64 vcc, 0x80000
	s_cmp_eq_u32 s79, s77
	v_lshl_add_u64 v[190:191], v[190:191], 0, vcc
	s_branch .Lat_step_end
.LBB0_309:
	s_sub_i32 s73, 0, s73
	v_add_u32_e32 v0, s73, v213
	s_add_i32 s77, s77, 1
	s_waitcnt vmcnt(3)
	ds_write_b128 v0, v[2:5] offset:37888
	s_waitcnt vmcnt(2)
	ds_write_b128 v0, v[6:9] offset:46592
	v_add_u32_e32 v0, s73, v214
	s_mov_b64 vcc, 0x80000
	v_add_u32_e32 v2, 0xd800, v0
	v_add_u32_e32 v0, 0x10000, v0
	v_lshl_add_u64 v[188:189], v[188:189], 0, 64
	s_cmp_eq_u32 s79, s77
	v_lshl_add_u64 v[190:191], v[190:191], 0, vcc
	s_waitcnt vmcnt(1)
	ds_write2_b64 v2, v[10:11], v[12:13] offset1:2
	s_waitcnt vmcnt(0)
	ds_write2_b64 v0, v[176:177], v[178:179] offset1:2

.Lat_nostag:
	v_lshl_add_u64 v[2:3], s[30:31], 0, v[190:191]
	s_mov_b32 s73, 0x13481000
	v_add_co_u32_e32 v6, vcc, s73, v2
	v_lshl_add_u64 v[10:11], s[30:31], 0, v[188:189]
	s_nop 0
	v_addc_co_u32_e32 v7, vcc, 0, v3, vcc
	v_add_co_u32_e32 v12, vcc, 0x1f400000, v10
	global_load_dwordx4 v[2:5], v[6:7], off
	s_nop 0
	global_load_dwordx4 v[6:9], v[6:7], off offset:256
	v_addc_co_u32_e32 v13, vcc, 0, v11, vcc
	v_add_co_u32_e32 v14, vcc, 0x1f480000, v10
	s_bitcmp1_b32 s77, 0
	s_nop 0
	v_addc_co_u32_e32 v15, vcc, 0, v11, vcc
	global_load_dwordx4 v[10:13], v[12:13], off offset:64
	s_nop 0
	global_load_dwordx4 v[176:179], v[14:15], off offset:64
	s_cselect_b32 s73, 0x9400, 0
	s_cmp_gt_u32 s77, s49
	s_cbranch_scc1 .LBB0_309
	s_add_i32 vcc_lo, s73, 0
	s_add_i32 vcc_hi, vcc_lo, s78
	v_add3_u32 v0, vcc_hi, v211, v209
	v_add_u32_e32 v14, v210, v209
	ds_read_b128 v[144:147], v0
	ds_read_b128 v[160:163], v0 offset:32
	ds_read_b128 v[148:151], v14
	ds_read_b128 v[164:167], v14 offset:32
	ds_read_b128 v[216:219], v0 offset:64
	ds_read_b128 v[220:223], v0 offset:96
	ds_read_b128 v[224:227], v14 offset:64
	ds_read_b128 v[228:231], v14 offset:96
	v_add_u32_e32 v250, vcc_lo, v212
	s_waitcnt lgkmcnt(5)
	v_mfma_f32_32x32x16_bf16 v[144:159], v[144:147], v[148:151], 0
	s_waitcnt lgkmcnt(4)
	v_mfma_f32_32x32x16_bf16 v[160:175], v[160:163], v[164:167], 0
	s_waitcnt lgkmcnt(1)
	v_mfma_f32_32x32x16_bf16 v[144:159], v[216:219], v[224:227], v[144:159]
	ds_read_b128 v[216:219], v0 offset:128
	ds_read_b128 v[224:227], v0 offset:160
	ds_read_b128 v[232:235], v14 offset:128
	ds_read_b128 v[236:239], v14 offset:160
	ds_read_b128 v[240:243], v0 offset:192
	ds_read_b128 v[244:247], v0 offset:224
	ds_read_b128 v[180:183], v14 offset:192
	ds_read_b128 v[184:187], v14 offset:224
	s_waitcnt lgkmcnt(8)
	v_mfma_f32_32x32x16_bf16 v[160:175], v[220:223], v[228:231], v[160:175]
	s_waitcnt lgkmcnt(5)
	v_mfma_f32_32x32x16_bf16 v[144:159], v[216:219], v[232:235], v[144:159]
	s_waitcnt lgkmcnt(4)
	v_mfma_f32_32x32x16_bf16 v[160:175], v[224:227], v[236:239], v[160:175]
	s_waitcnt lgkmcnt(1)
	v_mfma_f32_32x32x16_bf16 v[144:159], v[240:243], v[180:183], v[144:159]
	s_waitcnt lgkmcnt(0)
	v_mfma_f32_32x32x16_bf16 v[160:175], v[244:247], v[184:187], v[160:175]
	s_nop 11
	v_pk_add_f32 v[14:15], v[158:159], v[174:175]
	v_add_u32_e32 v174, v250, v208
	v_add_u32_e32 v0, 0x4000, v174
	v_pk_add_f32 v[166:167], v[150:151], v[166:167]
	v_pk_add_f32 v[164:165], v[148:149], v[164:165]
	v_pk_add_f32 v[162:163], v[146:147], v[162:163]
	v_pk_add_f32 v[160:161], v[144:145], v[160:161]
	ds_read_b128 v[148:151], v174 offset:17408
	ds_read_b128 v[144:147], v174 offset:17440
	v_add_u32_e32 v0, 0x4800, v174
	v_pk_add_f32 v[172:173], v[156:157], v[172:173]
	v_pk_add_f32 v[170:171], v[154:155], v[170:171]
	v_pk_add_f32 v[168:169], v[152:153], v[168:169]
	ds_read_b128 v[156:159], v174 offset:19968
	ds_read_b128 v[152:155], v174 offset:20000
	s_cmp_lg_u32 s49, s77
	s_cbranch_scc1 .LBB0_313
	v_cndmask_b32_e64 v0, v160, v202, s[90:91]
	v_cndmask_b32_e64 v161, v202, v161, s[88:89]
	v_cndmask_b32_e64 v160, v0, v160, s[88:89]
	v_cndmask_b32_e64 v162, v162, v202, s[92:93]
	v_cndmask_b32_e64 v163, v163, v202, s[94:95]
	v_cndmask_b32_e64 v164, v164, v202, s[96:97]
	v_cndmask_b32_e64 v165, v165, v202, s[4:5]
	v_cndmask_b32_e64 v166, v166, v202, s[6:7]
	v_cndmask_b32_e64 v167, v167, v202, s[8:9]
	v_cndmask_b32_e64 v168, v168, v202, s[10:11]
	v_cndmask_b32_e64 v169, v169, v202, s[12:13]
	v_cndmask_b32_e64 v170, v170, v202, s[14:15]
	v_cndmask_b32_e64 v171, v171, v202, s[16:17]
	v_cndmask_b32_e64 v172, v172, v202, s[18:19]
	v_cndmask_b32_e64 v173, v173, v202, s[20:21]
	v_cndmask_b32_e64 v14, v14, v202, s[22:23]
	v_cndmask_b32_e64 v15, v15, v202, s[24:25]

.LBB0_315:
	s_or_b32 s28, s28, 2
	s_cmp_ge_u32 s28, s49
	s_cbranch_scc1 .LBB0_321
	s_bitcmp1_b32 s79, 0
	s_cselect_b32 s28, 0x9400, 0
	s_add_i32 s28, s28, 0
	s_add_i32 s73, s28, s78
	v_add3_u32 v0, s73, v211, v209
	v_add_u32_e32 v180, s28, v212
	v_add_u32_e32 v14, v210, v209
	ds_read_b128 v[2:5], v0
	ds_read_b128 v[6:9], v0 offset:32
	ds_read_b128 v[10:13], v14
	ds_read_b128 v[160:163], v14 offset:32
	ds_read_b128 v[176:179], v0 offset:64
	ds_read_b128 v[188:191], v14 offset:64
	ds_read_b128 v[210:213], v0 offset:96
	ds_read_b128 v[216:219], v14 offset:96
	s_waitcnt lgkmcnt(5)
	v_mfma_f32_32x32x16_bf16 v[144:159], v[2:5], v[10:13], 0
	s_waitcnt lgkmcnt(4)
	v_mfma_f32_32x32x16_bf16 v[160:175], v[6:9], v[160:163], 0
	s_waitcnt lgkmcnt(2)
	v_mfma_f32_32x32x16_bf16 v[144:159], v[176:179], v[188:191], v[144:159]
	ds_read_b128 v[2:5], v0 offset:128
	ds_read_b128 v[6:9], v0 offset:160
	ds_read_b128 v[10:13], v14 offset:128
	ds_read_b128 v[176:179], v14 offset:160
	ds_read_b128 v[188:191], v0 offset:192
	ds_read_b128 v[220:223], v0 offset:224
	ds_read_b128 v[224:227], v14 offset:192
	ds_read_b128 v[228:231], v14 offset:224
	s_waitcnt lgkmcnt(8)
	v_mfma_f32_32x32x16_bf16 v[160:175], v[210:213], v[216:219], v[160:175]
	s_waitcnt lgkmcnt(5)
	v_mfma_f32_32x32x16_bf16 v[144:159], v[2:5], v[10:13], v[144:159]
	s_waitcnt lgkmcnt(4)
	v_mfma_f32_32x32x16_bf16 v[160:175], v[6:9], v[176:179], v[160:175]
	s_waitcnt lgkmcnt(1)
	v_mfma_f32_32x32x16_bf16 v[144:159], v[188:191], v[224:227], v[144:159]
	s_waitcnt lgkmcnt(0)
	v_mfma_f32_32x32x16_bf16 v[160:175], v[220:223], v[228:231], v[160:175]
	s_nop 11
	v_pk_add_f32 v[14:15], v[158:159], v[174:175]
	v_pk_add_f32 v[158:159], v[146:147], v[162:163]
	v_add_u32_e32 v162, v180, v208
	v_add_u32_e32 v0, 0x4000, v162
	ds_read_b128 v[6:9], v162 offset:17408
	ds_read_b128 v[2:5], v162 offset:17440
	v_add_u32_e32 v0, 0x4800, v162
	v_pk_add_f32 v[160:161], v[144:145], v[160:161]
	ds_read_b128 v[144:147], v162 offset:19968
	ds_read_b128 v[10:13], v162 offset:20000
	v_pk_add_f32 v[156:157], v[156:157], v[172:173]
	v_pk_add_f32 v[154:155], v[154:155], v[170:171]
	v_pk_add_f32 v[152:153], v[152:153], v[168:169]
	v_pk_add_f32 v[150:151], v[150:151], v[166:167]
	v_pk_add_f32 v[148:149], v[148:149], v[164:165]
	s_cmp_lg_u32 s79, s49
	s_cbranch_scc1 .LBB0_318
	v_cndmask_b32_e64 v0, v160, v202, s[90:91]
	v_cndmask_b32_e64 v161, v202, v161, s[88:89]
	v_cndmask_b32_e64 v160, v0, v160, s[88:89]
	v_cndmask_b32_e64 v158, v158, v202, s[92:93]
	v_cndmask_b32_e64 v159, v159, v202, s[94:95]
	v_cndmask_b32_e64 v148, v148, v202, s[96:97]
	v_cndmask_b32_e64 v149, v149, v202, s[4:5]
	v_cndmask_b32_e64 v150, v150, v202, s[6:7]
	v_cndmask_b32_e64 v151, v151, v202, s[8:9]
	v_cndmask_b32_e64 v152, v152, v202, s[10:11]
	v_cndmask_b32_e64 v153, v153, v202, s[12:13]
	v_cndmask_b32_e64 v154, v154, v202, s[14:15]
	v_cndmask_b32_e64 v155, v155, v202, s[16:17]
	v_cndmask_b32_e64 v156, v156, v202, s[18:19]
	v_cndmask_b32_e64 v157, v157, v202, s[20:21]
	v_cndmask_b32_e64 v14, v14, v202, s[22:23]
	v_cndmask_b32_e64 v15, v15, v202, s[24:25]

.LBB0_320:
	v_sub_f32_e32 v0, v160, v215
	v_exp_f32_e32 v0, v0
	v_sub_f32_e32 v160, v161, v215
	v_exp_f32_e32 v160, v160
	v_sub_f32_e32 v158, v158, v215
	v_exp_f32_e32 v158, v158
	v_sub_f32_e32 v159, v159, v215
	v_exp_f32_e32 v159, v159
	v_sub_f32_e32 v148, v148, v215
	v_add_f32_e32 v161, v207, v0
	v_exp_f32_e32 v163, v148
	v_sub_f32_e32 v148, v149, v215
	v_add_f32_e32 v161, v160, v161
	v_exp_f32_e32 v164, v148
	v_sub_f32_e32 v148, v150, v215
	v_add_f32_e32 v161, v158, v161
	v_exp_f32_e32 v165, v148
	v_sub_f32_e32 v148, v151, v215
	v_add_f32_e32 v161, v159, v161
	v_exp_f32_e32 v151, v148
	v_add_f32_e32 v148, v163, v161
	v_add_f32_e32 v148, v164, v148
	v_add_f32_e32 v148, v165, v148
	v_add_f32_e32 v161, v151, v148
	v_cvt_pk_bf16_f32 v148, v0, v160
	v_sub_f32_e32 v0, v152, v215
	v_sub_f32_e32 v152, v153, v215
	v_cvt_pk_bf16_f32 v149, v158, v159
	v_exp_f32_e32 v158, v152
	v_sub_f32_e32 v152, v154, v215
	v_exp_f32_e32 v159, v152
	v_sub_f32_e32 v152, v155, v215
	v_exp_f32_e32 v160, v152
	v_sub_f32_e32 v152, v156, v215
	v_exp_f32_e32 v156, v152
	v_sub_f32_e32 v152, v157, v215
	v_sub_f32_e32 v14, v14, v215
	v_sub_f32_e32 v15, v15, v215
	v_cvt_pk_bf16_f32 v150, v163, v164
	v_cvt_pk_bf16_f32 v151, v165, v151
	v_exp_f32_e32 v0, v0
	v_exp_f32_e32 v157, v152
	v_exp_f32_e32 v14, v14
	v_exp_f32_e32 v15, v15
	v_cvt_pk_bf16_f32 v152, v0, v158
	v_cvt_pk_bf16_f32 v153, v159, v160
	v_cvt_pk_bf16_f32 v154, v156, v157
	v_cvt_pk_bf16_f32 v155, v14, v15
	s_waitcnt lgkmcnt(3)
	v_mfma_f32_32x32x16_bf16 v[128:143], v[6:9], v[148:151], v[128:143]
	s_waitcnt lgkmcnt(1)
	v_mfma_f32_32x32x16_bf16 v[112:127], v[144:147], v[148:151], v[112:127]
	v_add_u32_e32 v144, 0x5800, v162
	v_mfma_f32_32x32x16_bf16 v[128:143], v[2:5], v[152:155], v[128:143]
	ds_read_b128 v[2:5], v162 offset:25120
	s_waitcnt lgkmcnt(1)
	v_mfma_f32_32x32x16_bf16 v[112:127], v[10:13], v[152:155], v[112:127]
	v_add_u32_e32 v10, 0x5000, v162
	ds_read_b128 v[6:9], v162 offset:22528
	ds_read_b128 v[10:13], v162 offset:22560
	ds_read_b128 v[144:147], v162 offset:25088
	s_waitcnt lgkmcnt(2)
	v_mfma_f32_32x32x16_bf16 v[96:111], v[6:9], v[148:151], v[96:111]
	s_waitcnt lgkmcnt(0)
	v_mfma_f32_32x32x16_bf16 v[80:95], v[144:147], v[148:151], v[80:95]
	v_add_u32_e32 v144, 0x7000, v162
	v_mfma_f32_32x32x16_bf16 v[96:111], v[10:13], v[152:155], v[96:111]
	v_add_u32_e32 v10, 0x6800, v162
	v_mfma_f32_32x32x16_bf16 v[80:95], v[2:5], v[152:155], v[80:95]
	ds_read_b128 v[2:5], v162 offset:30240
	ds_read_b128 v[6:9], v162 offset:27648
	ds_read_b128 v[10:13], v162 offset:27680
	ds_read_b128 v[144:147], v162 offset:30208
	s_waitcnt lgkmcnt(2)
	v_mfma_f32_32x32x16_bf16 v[64:79], v[6:9], v[148:151], v[64:79]
	s_waitcnt lgkmcnt(0)
	v_mfma_f32_32x32x16_bf16 v[48:63], v[144:147], v[148:151], v[48:63]
	v_add_u32_e32 v144, 0x8000, v162
	v_mfma_f32_32x32x16_bf16 v[64:79], v[10:13], v[152:155], v[64:79]
	v_add_u32_e32 v10, 0x7800, v162
	v_mfma_f32_32x32x16_bf16 v[48:63], v[2:5], v[152:155], v[48:63]
	ds_read_b128 v[2:5], v162 offset:35360
	ds_read_b128 v[6:9], v162 offset:32768
	ds_read_b128 v[10:13], v162 offset:32800
	ds_read_b128 v[144:147], v162 offset:35328
	s_waitcnt lgkmcnt(2)
	v_mfma_f32_32x32x16_bf16 v[32:47], v[6:9], v[148:151], v[32:47]
	s_waitcnt lgkmcnt(0)
	v_mfma_f32_32x32x16_bf16 v[16:31], v[144:147], v[148:151], v[16:31]
	v_mfma_f32_32x32x16_bf16 v[32:47], v[10:13], v[152:155], v[32:47]
	v_mfma_f32_32x32x16_bf16 v[16:31], v[2:5], v[152:155], v[16:31]
	v_add_f32_e32 v0, v0, v161
	v_add_f32_e32 v0, v158, v0
	v_add_f32_e32 v0, v159, v0
	v_add_f32_e32 v0, v160, v0
	v_add_f32_e32 v0, v156, v0
	v_add_f32_e32 v0, v157, v0
	v_add_f32_e32 v0, v14, v0
	v_add_f32_e32 v207, v15, v0

.LBB0_323:
	s_andn2_b64 vcc, exec, s[42:43]
	s_waitcnt lgkmcnt(0)
	s_barrier
	s_cbranch_vccnz .LBB0_306
	v_div_scale_f32 v3, s[4:5], v0, v0, 1.0
	v_rcp_f32_e32 v4, v3
	s_mov_b64 s[4:5], 0x3000
	v_fma_f32 v5, -v3, v4, 1.0
	v_fmac_f32_e32 v4, v5, v4
	v_div_scale_f32 v5, vcc, 1.0, v0, 1.0
	v_mul_f32_e32 v6, v5, v4
	v_fma_f32 v7, -v3, v6, v5
	v_fmac_f32_e32 v6, v7, v4
	v_fma_f32 v3, -v3, v6, v5
	v_div_fmas_f32 v3, v3, v4, v6
	ds_read2st64_b32 v[232:233], v2 offset0:0 offset1:1
	ds_read2st64_b32 v[234:235], v2 offset0:2 offset1:3
	ds_read2st64_b32 v[236:237], v2 offset0:4 offset1:5
	ds_read2st64_b32 v[238:239], v2 offset0:6 offset1:7
	ds_read2st64_b32 v[240:241], v2 offset0:8 offset1:9
	ds_read2st64_b32 v[242:243], v2 offset0:10 offset1:11
	ds_read2st64_b32 v[244:245], v2 offset0:12 offset1:13
	ds_read2st64_b32 v[246:247], v2 offset0:14 offset1:15
	ds_read2st64_b32 v[208:209], v2 offset0:16 offset1:17
	ds_read2st64_b32 v[210:211], v2 offset0:18 offset1:19
	ds_read2st64_b32 v[212:213], v2 offset0:20 offset1:21
	ds_read2st64_b32 v[214:215], v2 offset0:22 offset1:23
	v_div_fixup_f32 v0, v3, v0, 1.0
	v_add_u32_e32 v10, s35, v195
	v_ashrrev_i32_e32 v11, 31, v10
	v_lshlrev_b64 v[8:9], 14, v[10:11]
	v_lshlrev_b64 v[10:11], 12, v[10:11]
	v_lshl_add_u64 v[8:9], s[52:53], 0, v[8:9]
	v_lshlrev_b32_e32 v6, 4, v205
	v_mov_b32_e32 v7, 0
	v_lshl_add_u64 v[8:9], v[8:9], 0, s[36:37]
	v_lshl_add_u64 v[10:11], s[58:59], 0, v[10:11]
	v_lshl_add_u64 v[8:9], v[8:9], 0, v[6:7]
	v_lshl_add_u64 v[10:11], v[10:11], 0, v[6:7]
	v_lshl_add_u64 v[8:9], v[8:9], 0, s[4:5]
	s_mov_b64 s[4:5], 0x8000
	global_load_dwordx4 v[144:147], v[8:9], off
	v_lshl_add_u64 v[8:9], v[8:9], 0, s[4:5]
	global_load_dwordx4 v[148:151], v[8:9], off
	v_lshl_add_u64 v[8:9], v[8:9], 0, s[4:5]
	global_load_dwordx4 v[152:155], v[8:9], off
	v_lshl_add_u64 v[8:9], v[8:9], 0, s[4:5]
	global_load_dwordx4 v[156:159], v[8:9], off
	v_lshl_add_u64 v[8:9], v[8:9], 0, s[4:5]
	global_load_dwordx4 v[160:163], v[8:9], off
	v_lshl_add_u64 v[8:9], v[8:9], 0, s[4:5]
	global_load_dwordx4 v[164:167], v[8:9], off
	v_lshl_add_u64 v[8:9], v[8:9], 0, s[4:5]
	global_load_dwordx4 v[168:171], v[8:9], off
	v_lshl_add_u64 v[8:9], v[8:9], 0, s[4:5]
	global_load_dwordx4 v[172:175], v[8:9], off
	v_lshl_add_u64 v[8:9], v[8:9], 0, s[4:5]
	global_load_dwordx4 v[176:179], v[8:9], off
	v_lshl_add_u64 v[8:9], v[8:9], 0, s[4:5]
	global_load_dwordx4 v[180:183], v[8:9], off
	v_lshl_add_u64 v[8:9], v[8:9], 0, s[4:5]
	global_load_dwordx4 v[184:187], v[8:9], off
	v_lshl_add_u64 v[8:9], v[8:9], 0, s[4:5]
	global_load_dwordx4 v[188:191], v[8:9], off
	v_lshl_add_u64 v[8:9], v[8:9], 0, s[4:5]
	global_load_dwordx4 v[216:219], v[8:9], off
	v_lshl_add_u64 v[8:9], v[8:9], 0, s[4:5]
	global_load_dwordx4 v[220:223], v[8:9], off
	v_lshl_add_u64 v[8:9], v[8:9], 0, s[4:5]
	global_load_dwordx4 v[224:227], v[8:9], off
	v_lshl_add_u64 v[8:9], v[8:9], 0, s[4:5]
	global_load_dwordx4 v[228:231], v[8:9], off
	v_mov_b32_e32 v12, 0
	v_mov_b32_e32 v13, 0
	v_mov_b32_e32 v14, 0
	v_mov_b32_e32 v15, 0
	s_waitcnt lgkmcnt(8)
	v_fma_f32 v128, v128, v0, -v232
	v_fma_f32 v129, v129, v0, -v233
	v_fma_f32 v130, v130, v0, -v234
	v_fma_f32 v131, v131, v0, -v235
	v_fma_f32 v132, v132, v0, -v236
	v_fma_f32 v133, v133, v0, -v237
	v_fma_f32 v134, v134, v0, -v238
	v_fma_f32 v135, v135, v0, -v239
	v_fmac_f32_e32 v12, v128, v128
	v_fmac_f32_e32 v13, v129, v129
	v_fmac_f32_e32 v14, v130, v130
	v_fmac_f32_e32 v15, v131, v131
	v_fmac_f32_e32 v12, v132, v132
	v_fmac_f32_e32 v13, v133, v133
	v_fmac_f32_e32 v14, v134, v134
	v_fmac_f32_e32 v15, v135, v135
	ds_read2st64_b32 v[232:233], v2 offset0:24 offset1:25
	ds_read2st64_b32 v[234:235], v2 offset0:26 offset1:27
	ds_read2st64_b32 v[236:237], v2 offset0:28 offset1:29
	ds_read2st64_b32 v[238:239], v2 offset0:30 offset1:31
	s_waitcnt lgkmcnt(8)
	v_fma_f32 v136, v136, v0, -v240
	v_fma_f32 v137, v137, v0, -v241
	v_fma_f32 v138, v138, v0, -v242
	v_fma_f32 v139, v139, v0, -v243
	v_fma_f32 v140, v140, v0, -v244
	v_fma_f32 v141, v141, v0, -v245
	v_fma_f32 v142, v142, v0, -v246
	v_fma_f32 v143, v143, v0, -v247
	v_fmac_f32_e32 v12, v136, v136
	v_fmac_f32_e32 v13, v137, v137
	v_fmac_f32_e32 v14, v138, v138
	v_fmac_f32_e32 v15, v139, v139
	v_fmac_f32_e32 v12, v140, v140
	v_fmac_f32_e32 v13, v141, v141
	v_fmac_f32_e32 v14, v142, v142
	v_fmac_f32_e32 v15, v143, v143
	ds_read2st64_b32 v[240:241], v2 offset0:32 offset1:33
	ds_read2st64_b32 v[242:243], v2 offset0:34 offset1:35
	ds_read2st64_b32 v[244:245], v2 offset0:36 offset1:37
	ds_read2st64_b32 v[246:247], v2 offset0:38 offset1:39
	s_waitcnt lgkmcnt(8)
	v_fma_f32 v112, v112, v0, -v208
	v_fma_f32 v113, v113, v0, -v209
	v_fma_f32 v114, v114, v0, -v210
	v_fma_f32 v115, v115, v0, -v211
	v_fma_f32 v116, v116, v0, -v212
	v_fma_f32 v117, v117, v0, -v213
	v_fma_f32 v118, v118, v0, -v214
	v_fma_f32 v119, v119, v0, -v215
	v_fmac_f32_e32 v12, v112, v112
	v_fmac_f32_e32 v13, v113, v113
	v_fmac_f32_e32 v14, v114, v114
	v_fmac_f32_e32 v15, v115, v115
	v_fmac_f32_e32 v12, v116, v116
	v_fmac_f32_e32 v13, v117, v117
	v_fmac_f32_e32 v14, v118, v118
	v_fmac_f32_e32 v15, v119, v119
	ds_read2st64_b32 v[208:209], v2 offset0:40 offset1:41
	ds_read2st64_b32 v[210:211], v2 offset0:42 offset1:43
	ds_read2st64_b32 v[212:213], v2 offset0:44 offset1:45
	ds_read2st64_b32 v[214:215], v2 offset0:46 offset1:47
	s_waitcnt lgkmcnt(8)
	v_fma_f32 v120, v120, v0, -v232
	v_fma_f32 v121, v121, v0, -v233
	v_fma_f32 v122, v122, v0, -v234
	v_fma_f32 v123, v123, v0, -v235
	v_fma_f32 v124, v124, v0, -v236
	v_fma_f32 v125, v125, v0, -v237
	v_fma_f32 v126, v126, v0, -v238
	v_fma_f32 v127, v127, v0, -v239
	v_fmac_f32_e32 v12, v120, v120
	v_fmac_f32_e32 v13, v121, v121
	v_fmac_f32_e32 v14, v122, v122
	v_fmac_f32_e32 v15, v123, v123
	v_fmac_f32_e32 v12, v124, v124
	v_fmac_f32_e32 v13, v125, v125
	v_fmac_f32_e32 v14, v126, v126
	v_fmac_f32_e32 v15, v127, v127
	ds_read2st64_b32 v[232:233], v2 offset0:48 offset1:49
	ds_read2st64_b32 v[234:235], v2 offset0:50 offset1:51
	ds_read2st64_b32 v[236:237], v2 offset0:52 offset1:53
	ds_read2st64_b32 v[238:239], v2 offset0:54 offset1:55
	s_waitcnt lgkmcnt(8)
	v_fma_f32 v96, v96, v0, -v240
	v_fma_f32 v97, v97, v0, -v241
	v_fma_f32 v98, v98, v0, -v242
	v_fma_f32 v99, v99, v0, -v243
	v_fma_f32 v100, v100, v0, -v244
	v_fma_f32 v101, v101, v0, -v245
	v_fma_f32 v102, v102, v0, -v246
	v_fma_f32 v103, v103, v0, -v247
	v_fmac_f32_e32 v12, v96, v96
	v_fmac_f32_e32 v13, v97, v97
	v_fmac_f32_e32 v14, v98, v98
	v_fmac_f32_e32 v15, v99, v99
	v_fmac_f32_e32 v12, v100, v100
	v_fmac_f32_e32 v13, v101, v101
	v_fmac_f32_e32 v14, v102, v102
	v_fmac_f32_e32 v15, v103, v103
	ds_read2st64_b32 v[240:241], v2 offset0:56 offset1:57
	ds_read2st64_b32 v[242:243], v2 offset0:58 offset1:59
	ds_read2st64_b32 v[244:245], v2 offset0:60 offset1:61
	ds_read2st64_b32 v[246:247], v2 offset0:62 offset1:63
	s_waitcnt lgkmcnt(8)
	v_fma_f32 v104, v104, v0, -v208
	v_fma_f32 v105, v105, v0, -v209
	v_fma_f32 v106, v106, v0, -v210
	v_fma_f32 v107, v107, v0, -v211
	v_fma_f32 v108, v108, v0, -v212
	v_fma_f32 v109, v109, v0, -v213
	v_fma_f32 v110, v110, v0, -v214
	v_fma_f32 v111, v111, v0, -v215
	v_fmac_f32_e32 v12, v104, v104
	v_fmac_f32_e32 v13, v105, v105
	v_fmac_f32_e32 v14, v106, v106
	v_fmac_f32_e32 v15, v107, v107
	v_fmac_f32_e32 v12, v108, v108
	v_fmac_f32_e32 v13, v109, v109
	v_fmac_f32_e32 v14, v110, v110
	v_fmac_f32_e32 v15, v111, v111
	ds_read2st64_b32 v[208:209], v2 offset0:64 offset1:65
	ds_read2st64_b32 v[210:211], v2 offset0:66 offset1:67
	ds_read2st64_b32 v[212:213], v2 offset0:68 offset1:69
	ds_read2st64_b32 v[214:215], v2 offset0:70 offset1:71
	s_waitcnt lgkmcnt(8)
	v_fma_f32 v80, v80, v0, -v232
	v_fma_f32 v81, v81, v0, -v233
	v_fma_f32 v82, v82, v0, -v234
	v_fma_f32 v83, v83, v0, -v235
	v_fma_f32 v84, v84, v0, -v236
	v_fma_f32 v85, v85, v0, -v237
	v_fma_f32 v86, v86, v0, -v238
	v_fma_f32 v87, v87, v0, -v239
	v_fmac_f32_e32 v12, v80, v80
	v_fmac_f32_e32 v13, v81, v81
	v_fmac_f32_e32 v14, v82, v82
	v_fmac_f32_e32 v15, v83, v83
	v_fmac_f32_e32 v12, v84, v84
	v_fmac_f32_e32 v13, v85, v85
	v_fmac_f32_e32 v14, v86, v86
	v_fmac_f32_e32 v15, v87, v87
	ds_read2st64_b32 v[232:233], v2 offset0:72 offset1:73
	ds_read2st64_b32 v[234:235], v2 offset0:74 offset1:75
	ds_read2st64_b32 v[236:237], v2 offset0:76 offset1:77
	ds_read2st64_b32 v[238:239], v2 offset0:78 offset1:79
	s_waitcnt lgkmcnt(8)
	v_fma_f32 v88, v88, v0, -v240
	v_fma_f32 v89, v89, v0, -v241
	v_fma_f32 v90, v90, v0, -v242
	v_fma_f32 v91, v91, v0, -v243
	v_fma_f32 v92, v92, v0, -v244
	v_fma_f32 v93, v93, v0, -v245
	v_fma_f32 v94, v94, v0, -v246
	v_fma_f32 v95, v95, v0, -v247
	v_fmac_f32_e32 v12, v88, v88
	v_fmac_f32_e32 v13, v89, v89
	v_fmac_f32_e32 v14, v90, v90
	v_fmac_f32_e32 v15, v91, v91
	v_fmac_f32_e32 v12, v92, v92
	v_fmac_f32_e32 v13, v93, v93
	v_fmac_f32_e32 v14, v94, v94
	v_fmac_f32_e32 v15, v95, v95
	ds_read2st64_b32 v[240:241], v2 offset0:80 offset1:81
	ds_read2st64_b32 v[242:243], v2 offset0:82 offset1:83
	ds_read2st64_b32 v[244:245], v2 offset0:84 offset1:85
	ds_read2st64_b32 v[246:247], v2 offset0:86 offset1:87
	s_waitcnt lgkmcnt(8)
	v_fma_f32 v64, v64, v0, -v208
	v_fma_f32 v65, v65, v0, -v209
	v_fma_f32 v66, v66, v0, -v210
	v_fma_f32 v67, v67, v0, -v211
	v_fma_f32 v68, v68, v0, -v212
	v_fma_f32 v69, v69, v0, -v213
	v_fma_f32 v70, v70, v0, -v214
	v_fma_f32 v71, v71, v0, -v215
	v_fmac_f32_e32 v12, v64, v64
	v_fmac_f32_e32 v13, v65, v65
	v_fmac_f32_e32 v14, v66, v66
	v_fmac_f32_e32 v15, v67, v67
	v_fmac_f32_e32 v12, v68, v68
	v_fmac_f32_e32 v13, v69, v69
	v_fmac_f32_e32 v14, v70, v70
	v_fmac_f32_e32 v15, v71, v71
	ds_read2st64_b32 v[208:209], v2 offset0:88 offset1:89
	ds_read2st64_b32 v[210:211], v2 offset0:90 offset1:91
	ds_read2st64_b32 v[212:213], v2 offset0:92 offset1:93
	ds_read2st64_b32 v[214:215], v2 offset0:94 offset1:95
	s_waitcnt lgkmcnt(8)
	v_fma_f32 v72, v72, v0, -v232
	v_fma_f32 v73, v73, v0, -v233
	v_fma_f32 v74, v74, v0, -v234
	v_fma_f32 v75, v75, v0, -v235
	v_fma_f32 v76, v76, v0, -v236
	v_fma_f32 v77, v77, v0, -v237
	v_fma_f32 v78, v78, v0, -v238
	v_fma_f32 v79, v79, v0, -v239
	v_fmac_f32_e32 v12, v72, v72
	v_fmac_f32_e32 v13, v73, v73
	v_fmac_f32_e32 v14, v74, v74
	v_fmac_f32_e32 v15, v75, v75
	v_fmac_f32_e32 v12, v76, v76
	v_fmac_f32_e32 v13, v77, v77
	v_fmac_f32_e32 v14, v78, v78
	v_fmac_f32_e32 v15, v79, v79
	ds_read2st64_b32 v[232:233], v2 offset0:96 offset1:97
	ds_read2st64_b32 v[234:235], v2 offset0:98 offset1:99
	ds_read2st64_b32 v[236:237], v2 offset0:100 offset1:101
	ds_read2st64_b32 v[238:239], v2 offset0:102 offset1:103
	s_waitcnt lgkmcnt(8)
	v_fma_f32 v48, v48, v0, -v240
	v_fma_f32 v49, v49, v0, -v241
	v_fma_f32 v50, v50, v0, -v242
	v_fma_f32 v51, v51, v0, -v243
	v_fma_f32 v52, v52, v0, -v244
	v_fma_f32 v53, v53, v0, -v245
	v_fma_f32 v54, v54, v0, -v246
	v_fma_f32 v55, v55, v0, -v247
	v_fmac_f32_e32 v12, v48, v48
	v_fmac_f32_e32 v13, v49, v49
	v_fmac_f32_e32 v14, v50, v50
	v_fmac_f32_e32 v15, v51, v51
	v_fmac_f32_e32 v12, v52, v52
	v_fmac_f32_e32 v13, v53, v53
	v_fmac_f32_e32 v14, v54, v54
	v_fmac_f32_e32 v15, v55, v55
	ds_read2st64_b32 v[240:241], v2 offset0:104 offset1:105
	ds_read2st64_b32 v[242:243], v2 offset0:106 offset1:107
	ds_read2st64_b32 v[244:245], v2 offset0:108 offset1:109
	ds_read2st64_b32 v[246:247], v2 offset0:110 offset1:111
	s_waitcnt lgkmcnt(8)
	v_fma_f32 v56, v56, v0, -v208
	v_fma_f32 v57, v57, v0, -v209
	v_fma_f32 v58, v58, v0, -v210
	v_fma_f32 v59, v59, v0, -v211
	v_fma_f32 v60, v60, v0, -v212
	v_fma_f32 v61, v61, v0, -v213
	v_fma_f32 v62, v62, v0, -v214
	v_fma_f32 v63, v63, v0, -v215
	v_fmac_f32_e32 v12, v56, v56
	v_fmac_f32_e32 v13, v57, v57
	v_fmac_f32_e32 v14, v58, v58
	v_fmac_f32_e32 v15, v59, v59
	v_fmac_f32_e32 v12, v60, v60
	v_fmac_f32_e32 v13, v61, v61
	v_fmac_f32_e32 v14, v62, v62
	v_fmac_f32_e32 v15, v63, v63
	ds_read2st64_b32 v[208:209], v2 offset0:112 offset1:113
	ds_read2st64_b32 v[210:211], v2 offset0:114 offset1:115
	ds_read2st64_b32 v[212:213], v2 offset0:116 offset1:117
	ds_read2st64_b32 v[214:215], v2 offset0:118 offset1:119
	s_waitcnt lgkmcnt(8)
	v_fma_f32 v32, v32, v0, -v232
	v_fma_f32 v33, v33, v0, -v233
	v_fma_f32 v34, v34, v0, -v234
	v_fma_f32 v35, v35, v0, -v235
	v_fma_f32 v36, v36, v0, -v236
	v_fma_f32 v37, v37, v0, -v237
	v_fma_f32 v38, v38, v0, -v238
	v_fma_f32 v39, v39, v0, -v239
	v_fmac_f32_e32 v12, v32, v32
	v_fmac_f32_e32 v13, v33, v33
	v_fmac_f32_e32 v14, v34, v34
	v_fmac_f32_e32 v15, v35, v35
	v_fmac_f32_e32 v12, v36, v36
	v_fmac_f32_e32 v13, v37, v37
	v_fmac_f32_e32 v14, v38, v38
	v_fmac_f32_e32 v15, v39, v39
	ds_read2st64_b32 v[232:233], v2 offset0:120 offset1:121
	ds_read2st64_b32 v[234:235], v2 offset0:122 offset1:123
	ds_read2st64_b32 v[236:237], v2 offset0:124 offset1:125
	ds_read2st64_b32 v[238:239], v2 offset0:126 offset1:127
	s_waitcnt lgkmcnt(8)
	v_fma_f32 v40, v40, v0, -v240
	v_fma_f32 v41, v41, v0, -v241
	v_fma_f32 v42, v42, v0, -v242
	v_fma_f32 v43, v43, v0, -v243
	v_fma_f32 v44, v44, v0, -v244
	v_fma_f32 v45, v45, v0, -v245
	v_fma_f32 v46, v46, v0, -v246
	v_fma_f32 v47, v47, v0, -v247
	v_fmac_f32_e32 v12, v40, v40
	v_fmac_f32_e32 v13, v41, v41
	v_fmac_f32_e32 v14, v42, v42
	v_fmac_f32_e32 v15, v43, v43
	v_fmac_f32_e32 v12, v44, v44
	v_fmac_f32_e32 v13, v45, v45
	v_fmac_f32_e32 v14, v46, v46
	v_fmac_f32_e32 v15, v47, v47
	s_waitcnt lgkmcnt(4)
	v_fma_f32 v16, v16, v0, -v208
	v_fma_f32 v17, v17, v0, -v209
	v_fma_f32 v18, v18, v0, -v210
	v_fma_f32 v19, v19, v0, -v211
	v_fma_f32 v20, v20, v0, -v212
	v_fma_f32 v21, v21, v0, -v213
	v_fma_f32 v22, v22, v0, -v214
	v_fma_f32 v23, v23, v0, -v215
	v_fmac_f32_e32 v12, v16, v16
	v_fmac_f32_e32 v13, v17, v17
	v_fmac_f32_e32 v14, v18, v18
	v_fmac_f32_e32 v15, v19, v19
	v_fmac_f32_e32 v12, v20, v20
	v_fmac_f32_e32 v13, v21, v21
	v_fmac_f32_e32 v14, v22, v22
	v_fmac_f32_e32 v15, v23, v23
	s_waitcnt lgkmcnt(0)
	v_fma_f32 v24, v24, v0, -v232
	v_fma_f32 v25, v25, v0, -v233
	v_fma_f32 v26, v26, v0, -v234
	v_fma_f32 v27, v27, v0, -v235
	v_fma_f32 v28, v28, v0, -v236
	v_fma_f32 v29, v29, v0, -v237
	v_fma_f32 v30, v30, v0, -v238
	v_fma_f32 v31, v31, v0, -v239
	v_fmac_f32_e32 v12, v24, v24
	v_fmac_f32_e32 v13, v25, v25
	v_fmac_f32_e32 v14, v26, v26
	v_fmac_f32_e32 v15, v27, v27
	v_fmac_f32_e32 v12, v28, v28
	v_fmac_f32_e32 v13, v29, v29
	v_fmac_f32_e32 v14, v30, v30
	v_fmac_f32_e32 v15, v31, v31
	v_lshlrev_b32_e32 v2, 4, v195
	v_add_u32_e32 v2, 0x23800, v2
	ds_read_b128 v[232:235], v2 offset:0
	ds_read_b128 v[236:239], v2 offset:32
	ds_read_b128 v[240:243], v2 offset:64
	ds_read_b128 v[244:247], v2 offset:96
	ds_read_b128 v[208:211], v2 offset:128
	ds_read_b128 v[212:215], v2 offset:160
	v_add_f32_e32 v12, v12, v13
	v_add_f32_e32 v14, v14, v15
	v_add_f32_e32 v12, v12, v14
	v_mov_b32_e32 v13, v12
	s_nop 1
	v_permlane32_swap_b32_e32 v12, v13
	v_add_f32_e32 v12, v12, v13
	v_mov_b32_e32 v13, 0x3727c5ac
	v_fmamk_f32 v12, v12, 0x3b800000, v13
	v_cmp_gt_f32_e32 vcc, s81, v12
	v_mul_f32_e32 v13, 0x4b800000, v12
	s_nop 0
	v_cndmask_b32_e32 v12, v12, v13, vcc
	v_rsq_f32_e32 v12, v12
	s_nop 0
	v_mul_f32_e32 v13, 0x45800000, v12
	v_cndmask_b32_e32 v12, v12, v13, vcc
	v_mul_f32_e32 v0, v194, v12
	v_and_b32_e32 v3, 7, v205
	v_xor_b32_e32 v3, v3, v195
	v_lshlrev_b32_e32 v3, 4, v3
	v_lshl_add_u32 v3, v205, 10, v3
	v_add_u32_e32 v3, s76, v3
	v_lshlrev_b32_e32 v9, 5, v205
	v_lshlrev_b32_e32 v8, 4, v195
	v_xor_b32_e32 v9, v9, v8
	v_lshl_add_u32 v9, v195, 10, v9
	v_add_u32_e32 v9, s76, v9
	s_waitcnt lgkmcnt(4)
	v_mul_f32_e32 v4, v128, v0
	v_mul_f32_e32 v5, v129, v0
	v_mul_f32_e32 v6, v130, v0
	v_mul_f32_e32 v7, v131, v0
	v_mul_f32_e32 v4, v232, v4
	v_mul_f32_e32 v5, v233, v5
	v_mul_f32_e32 v6, v234, v6
	v_mul_f32_e32 v7, v235, v7
	ds_write_b128 v3, v[4:7]
	v_mul_f32_e32 v12, v132, v0
	v_mul_f32_e32 v13, v133, v0
	v_mul_f32_e32 v14, v134, v0
	v_mul_f32_e32 v15, v135, v0
	v_mul_f32_e32 v12, v236, v12
	v_mul_f32_e32 v13, v237, v13
	v_mul_f32_e32 v14, v238, v14
	v_mul_f32_e32 v15, v239, v15
	v_xor_b32_e32 v8, 0x20, v3
	ds_write_b128 v8, v[12:15]
	ds_read_b128 v[232:235], v2 offset:192
	ds_read_b128 v[236:239], v2 offset:224
	s_waitcnt lgkmcnt(6)
	v_mul_f32_e32 v4, v136, v0
	v_mul_f32_e32 v5, v137, v0
	v_mul_f32_e32 v6, v138, v0
	v_mul_f32_e32 v7, v139, v0
	v_mul_f32_e32 v4, v240, v4
	v_mul_f32_e32 v5, v241, v5
	v_mul_f32_e32 v6, v242, v6
	v_mul_f32_e32 v7, v243, v7
	v_xor_b32_e32 v8, 0x40, v3
	ds_write_b128 v8, v[4:7]
	v_mul_f32_e32 v12, v140, v0
	v_mul_f32_e32 v13, v141, v0
	v_mul_f32_e32 v14, v142, v0
	v_mul_f32_e32 v15, v143, v0
	v_mul_f32_e32 v12, v244, v12
	v_mul_f32_e32 v13, v245, v13
	v_mul_f32_e32 v14, v246, v14
	v_mul_f32_e32 v15, v247, v15
	v_xor_b32_e32 v8, 0x60, v3
	ds_write_b128 v8, v[12:15]
	ds_read_b128 v[240:243], v2 offset:256
	ds_read_b128 v[244:247], v2 offset:288
	s_waitcnt lgkmcnt(8)
	v_mul_f32_e32 v4, v112, v0
	v_mul_f32_e32 v5, v113, v0
	v_mul_f32_e32 v6, v114, v0
	v_mul_f32_e32 v7, v115, v0
	v_mul_f32_e32 v4, v208, v4
	v_mul_f32_e32 v5, v209, v5
	v_mul_f32_e32 v6, v210, v6
	v_mul_f32_e32 v7, v211, v7
	v_xor_b32_e32 v8, 0x80, v3
	ds_write_b128 v8, v[4:7]
	v_mul_f32_e32 v12, v116, v0
	v_mul_f32_e32 v13, v117, v0
	v_mul_f32_e32 v14, v118, v0
	v_mul_f32_e32 v15, v119, v0
	v_mul_f32_e32 v12, v212, v12
	v_mul_f32_e32 v13, v213, v13
	v_mul_f32_e32 v14, v214, v14
	v_mul_f32_e32 v15, v215, v15
	v_xor_b32_e32 v8, 0xa0, v3
	ds_write_b128 v8, v[12:15]
	ds_read_b128 v[208:211], v2 offset:320
	ds_read_b128 v[212:215], v2 offset:352
	s_waitcnt lgkmcnt(8)
	v_mul_f32_e32 v4, v120, v0
	v_mul_f32_e32 v5, v121, v0
	v_mul_f32_e32 v6, v122, v0
	v_mul_f32_e32 v7, v123, v0
	v_mul_f32_e32 v4, v232, v4
	v_mul_f32_e32 v5, v233, v5
	v_mul_f32_e32 v6, v234, v6
	v_mul_f32_e32 v7, v235, v7
	v_xor_b32_e32 v8, 0xc0, v3
	ds_write_b128 v8, v[4:7]
	v_mul_f32_e32 v12, v124, v0
	v_mul_f32_e32 v13, v125, v0
	v_mul_f32_e32 v14, v126, v0
	v_mul_f32_e32 v15, v127, v0
	v_mul_f32_e32 v12, v236, v12
	v_mul_f32_e32 v13, v237, v13
	v_mul_f32_e32 v14, v238, v14
	v_mul_f32_e32 v15, v239, v15
	v_xor_b32_e32 v8, 0xe0, v3
	ds_write_b128 v8, v[12:15]
	ds_read_b128 v[232:235], v2 offset:384
	ds_read_b128 v[236:239], v2 offset:416
	s_waitcnt lgkmcnt(8)
	v_mul_f32_e32 v4, v96, v0
	v_mul_f32_e32 v5, v97, v0
	v_mul_f32_e32 v6, v98, v0
	v_mul_f32_e32 v7, v99, v0
	v_mul_f32_e32 v4, v240, v4
	v_mul_f32_e32 v5, v241, v5
	v_mul_f32_e32 v6, v242, v6
	v_mul_f32_e32 v7, v243, v7
	v_xor_b32_e32 v8, 0x100, v3
	ds_write_b128 v8, v[4:7]
	v_mul_f32_e32 v12, v100, v0
	v_mul_f32_e32 v13, v101, v0
	v_mul_f32_e32 v14, v102, v0
	v_mul_f32_e32 v15, v103, v0
	v_mul_f32_e32 v12, v244, v12
	v_mul_f32_e32 v13, v245, v13
	v_mul_f32_e32 v14, v246, v14
	v_mul_f32_e32 v15, v247, v15
	v_xor_b32_e32 v8, 0x120, v3
	ds_write_b128 v8, v[12:15]
	ds_read_b128 v[240:243], v2 offset:448
	ds_read_b128 v[244:247], v2 offset:480
	s_waitcnt lgkmcnt(8)
	v_mul_f32_e32 v4, v104, v0
	v_mul_f32_e32 v5, v105, v0
	v_mul_f32_e32 v6, v106, v0
	v_mul_f32_e32 v7, v107, v0
	v_mul_f32_e32 v4, v208, v4
	v_mul_f32_e32 v5, v209, v5
	v_mul_f32_e32 v6, v210, v6
	v_mul_f32_e32 v7, v211, v7
	v_xor_b32_e32 v8, 0x140, v3
	ds_write_b128 v8, v[4:7]
	v_mul_f32_e32 v12, v108, v0
	v_mul_f32_e32 v13, v109, v0
	v_mul_f32_e32 v14, v110, v0
	v_mul_f32_e32 v15, v111, v0
	v_mul_f32_e32 v12, v212, v12
	v_mul_f32_e32 v13, v213, v13
	v_mul_f32_e32 v14, v214, v14
	v_mul_f32_e32 v15, v215, v15
	v_xor_b32_e32 v8, 0x160, v3
	ds_write_b128 v8, v[12:15]
	ds_read_b128 v[208:211], v2 offset:512
	ds_read_b128 v[212:215], v2 offset:544
	s_waitcnt lgkmcnt(8)
	v_mul_f32_e32 v4, v80, v0
	v_mul_f32_e32 v5, v81, v0
	v_mul_f32_e32 v6, v82, v0
	v_mul_f32_e32 v7, v83, v0
	v_mul_f32_e32 v4, v232, v4
	v_mul_f32_e32 v5, v233, v5
	v_mul_f32_e32 v6, v234, v6
	v_mul_f32_e32 v7, v235, v7
	v_xor_b32_e32 v8, 0x180, v3
	ds_write_b128 v8, v[4:7]
	v_mul_f32_e32 v12, v84, v0
	v_mul_f32_e32 v13, v85, v0
	v_mul_f32_e32 v14, v86, v0
	v_mul_f32_e32 v15, v87, v0
	v_mul_f32_e32 v12, v236, v12
	v_mul_f32_e32 v13, v237, v13
	v_mul_f32_e32 v14, v238, v14
	v_mul_f32_e32 v15, v239, v15
	v_xor_b32_e32 v8, 0x1a0, v3
	ds_write_b128 v8, v[12:15]
	ds_read_b128 v[232:235], v2 offset:576
	ds_read_b128 v[236:239], v2 offset:608
	s_waitcnt lgkmcnt(8)
	v_mul_f32_e32 v4, v88, v0
	v_mul_f32_e32 v5, v89, v0
	v_mul_f32_e32 v6, v90, v0
	v_mul_f32_e32 v7, v91, v0
	v_mul_f32_e32 v4, v240, v4
	v_mul_f32_e32 v5, v241, v5
	v_mul_f32_e32 v6, v242, v6
	v_mul_f32_e32 v7, v243, v7
	v_xor_b32_e32 v8, 0x1c0, v3
	ds_write_b128 v8, v[4:7]
	v_mul_f32_e32 v12, v92, v0
	v_mul_f32_e32 v13, v93, v0
	v_mul_f32_e32 v14, v94, v0
	v_mul_f32_e32 v15, v95, v0
	v_mul_f32_e32 v12, v244, v12
	v_mul_f32_e32 v13, v245, v13
	v_mul_f32_e32 v14, v246, v14
	v_mul_f32_e32 v15, v247, v15
	v_xor_b32_e32 v8, 0x1e0, v3
	ds_write_b128 v8, v[12:15]
	ds_read_b128 v[240:243], v2 offset:640
	ds_read_b128 v[244:247], v2 offset:672
	s_waitcnt lgkmcnt(8)
	v_mul_f32_e32 v4, v64, v0
	v_mul_f32_e32 v5, v65, v0
	v_mul_f32_e32 v6, v66, v0
	v_mul_f32_e32 v7, v67, v0
	v_mul_f32_e32 v4, v208, v4
	v_mul_f32_e32 v5, v209, v5
	v_mul_f32_e32 v6, v210, v6
	v_mul_f32_e32 v7, v211, v7
	v_xor_b32_e32 v8, 0x200, v3
	ds_write_b128 v8, v[4:7]
	v_mul_f32_e32 v12, v68, v0
	v_mul_f32_e32 v13, v69, v0
	v_mul_f32_e32 v14, v70, v0
	v_mul_f32_e32 v15, v71, v0
	v_mul_f32_e32 v12, v212, v12
	v_mul_f32_e32 v13, v213, v13
	v_mul_f32_e32 v14, v214, v14
	v_mul_f32_e32 v15, v215, v15
	v_xor_b32_e32 v8, 0x220, v3
	ds_write_b128 v8, v[12:15]
	ds_read_b128 v[208:211], v2 offset:704
	ds_read_b128 v[212:215], v2 offset:736
	s_waitcnt lgkmcnt(8)
	v_mul_f32_e32 v4, v72, v0
	v_mul_f32_e32 v5, v73, v0
	v_mul_f32_e32 v6, v74, v0
	v_mul_f32_e32 v7, v75, v0
	v_mul_f32_e32 v4, v232, v4
	v_mul_f32_e32 v5, v233, v5
	v_mul_f32_e32 v6, v234, v6
	v_mul_f32_e32 v7, v235, v7
	v_xor_b32_e32 v8, 0x240, v3
	ds_write_b128 v8, v[4:7]
	v_mul_f32_e32 v12, v76, v0
	v_mul_f32_e32 v13, v77, v0
	v_mul_f32_e32 v14, v78, v0
	v_mul_f32_e32 v15, v79, v0
	v_mul_f32_e32 v12, v236, v12
	v_mul_f32_e32 v13, v237, v13
	v_mul_f32_e32 v14, v238, v14
	v_mul_f32_e32 v15, v239, v15
	v_xor_b32_e32 v8, 0x260, v3
	ds_write_b128 v8, v[12:15]
	ds_read_b128 v[232:235], v2 offset:768
	ds_read_b128 v[236:239], v2 offset:800
	s_waitcnt lgkmcnt(8)
	v_mul_f32_e32 v4, v48, v0
	v_mul_f32_e32 v5, v49, v0
	v_mul_f32_e32 v6, v50, v0
	v_mul_f32_e32 v7, v51, v0
	v_mul_f32_e32 v4, v240, v4
	v_mul_f32_e32 v5, v241, v5
	v_mul_f32_e32 v6, v242, v6
	v_mul_f32_e32 v7, v243, v7
	v_xor_b32_e32 v8, 0x280, v3
	ds_write_b128 v8, v[4:7]
	v_mul_f32_e32 v12, v52, v0
	v_mul_f32_e32 v13, v53, v0
	v_mul_f32_e32 v14, v54, v0
	v_mul_f32_e32 v15, v55, v0
	v_mul_f32_e32 v12, v244, v12
	v_mul_f32_e32 v13, v245, v13
	v_mul_f32_e32 v14, v246, v14
	v_mul_f32_e32 v15, v247, v15
	v_xor_b32_e32 v8, 0x2a0, v3
	ds_write_b128 v8, v[12:15]
	ds_read_b128 v[240:243], v2 offset:832
	ds_read_b128 v[244:247], v2 offset:864
	s_waitcnt lgkmcnt(8)
	v_mul_f32_e32 v4, v56, v0
	v_mul_f32_e32 v5, v57, v0
	v_mul_f32_e32 v6, v58, v0
	v_mul_f32_e32 v7, v59, v0
	v_mul_f32_e32 v4, v208, v4
	v_mul_f32_e32 v5, v209, v5
	v_mul_f32_e32 v6, v210, v6
	v_mul_f32_e32 v7, v211, v7
	v_xor_b32_e32 v8, 0x2c0, v3
	ds_write_b128 v8, v[4:7]
	v_mul_f32_e32 v12, v60, v0
	v_mul_f32_e32 v13, v61, v0
	v_mul_f32_e32 v14, v62, v0
	v_mul_f32_e32 v15, v63, v0
	v_mul_f32_e32 v12, v212, v12
	v_mul_f32_e32 v13, v213, v13
	v_mul_f32_e32 v14, v214, v14
	v_mul_f32_e32 v15, v215, v15
	v_xor_b32_e32 v8, 0x2e0, v3
	ds_write_b128 v8, v[12:15]
	ds_read_b128 v[208:211], v2 offset:896
	ds_read_b128 v[212:215], v2 offset:928
	s_waitcnt lgkmcnt(8)
	v_mul_f32_e32 v4, v32, v0
	v_mul_f32_e32 v5, v33, v0
	v_mul_f32_e32 v6, v34, v0
	v_mul_f32_e32 v7, v35, v0
	v_mul_f32_e32 v4, v232, v4
	v_mul_f32_e32 v5, v233, v5
	v_mul_f32_e32 v6, v234, v6
	v_mul_f32_e32 v7, v235, v7
	v_xor_b32_e32 v8, 0x300, v3
	ds_write_b128 v8, v[4:7]
	v_mul_f32_e32 v12, v36, v0
	v_mul_f32_e32 v13, v37, v0
	v_mul_f32_e32 v14, v38, v0
	v_mul_f32_e32 v15, v39, v0
	v_mul_f32_e32 v12, v236, v12
	v_mul_f32_e32 v13, v237, v13
	v_mul_f32_e32 v14, v238, v14
	v_mul_f32_e32 v15, v239, v15
	v_xor_b32_e32 v8, 0x320, v3
	ds_write_b128 v8, v[12:15]
	ds_read_b128 v[232:235], v2 offset:960
	ds_read_b128 v[236:239], v2 offset:992
	s_waitcnt lgkmcnt(8)
	v_mul_f32_e32 v4, v40, v0
	v_mul_f32_e32 v5, v41, v0
	v_mul_f32_e32 v6, v42, v0
	v_mul_f32_e32 v7, v43, v0
	v_mul_f32_e32 v4, v240, v4
	v_mul_f32_e32 v5, v241, v5
	v_mul_f32_e32 v6, v242, v6
	v_mul_f32_e32 v7, v243, v7
	v_xor_b32_e32 v8, 0x340, v3
	ds_write_b128 v8, v[4:7]
	v_mul_f32_e32 v12, v44, v0
	v_mul_f32_e32 v13, v45, v0
	v_mul_f32_e32 v14, v46, v0
	v_mul_f32_e32 v15, v47, v0
	v_mul_f32_e32 v12, v244, v12
	v_mul_f32_e32 v13, v245, v13
	v_mul_f32_e32 v14, v246, v14
	v_mul_f32_e32 v15, v247, v15
	v_xor_b32_e32 v8, 0x360, v3
	ds_write_b128 v8, v[12:15]
	s_waitcnt lgkmcnt(6)
	v_mul_f32_e32 v4, v16, v0
	v_mul_f32_e32 v5, v17, v0
	v_mul_f32_e32 v6, v18, v0
	v_mul_f32_e32 v7, v19, v0
	v_mul_f32_e32 v4, v208, v4
	v_mul_f32_e32 v5, v209, v5
	v_mul_f32_e32 v6, v210, v6
	v_mul_f32_e32 v7, v211, v7
	v_xor_b32_e32 v8, 0x380, v3
	ds_write_b128 v8, v[4:7]
	v_mul_f32_e32 v12, v20, v0
	v_mul_f32_e32 v13, v21, v0
	v_mul_f32_e32 v14, v22, v0
	v_mul_f32_e32 v15, v23, v0
	v_mul_f32_e32 v12, v212, v12
	v_mul_f32_e32 v13, v213, v13
	v_mul_f32_e32 v14, v214, v14
	v_mul_f32_e32 v15, v215, v15
	v_xor_b32_e32 v8, 0x3a0, v3
	ds_write_b128 v8, v[12:15]
	s_waitcnt lgkmcnt(4)
	v_mul_f32_e32 v4, v24, v0
	v_mul_f32_e32 v5, v25, v0
	v_mul_f32_e32 v6, v26, v0
	v_mul_f32_e32 v7, v27, v0
	v_mul_f32_e32 v4, v232, v4
	v_mul_f32_e32 v5, v233, v5
	v_mul_f32_e32 v6, v234, v6
	v_mul_f32_e32 v7, v235, v7
	v_xor_b32_e32 v8, 0x3c0, v3
	ds_write_b128 v8, v[4:7]
	v_mul_f32_e32 v12, v28, v0
	v_mul_f32_e32 v13, v29, v0
	v_mul_f32_e32 v14, v30, v0
	v_mul_f32_e32 v15, v31, v0
	v_mul_f32_e32 v12, v236, v12
	v_mul_f32_e32 v13, v237, v13
	v_mul_f32_e32 v14, v238, v14
	v_mul_f32_e32 v15, v239, v15
	v_xor_b32_e32 v8, 0x3e0, v3
	ds_write_b128 v8, v[12:15]
	s_waitcnt lgkmcnt(0)
	s_mov_b64 s[4:5], 0x2000
	v_xor_b32_e32 v8, 16, v9
	ds_read_b128 v[232:235], v9 offset:0
	ds_read_b128 v[236:239], v8 offset:0
	v_xor_b32_e32 v2, 0x20, v9
	v_xor_b32_e32 v8, 0x30, v9
	ds_read_b128 v[240:243], v2 offset:2048
	ds_read_b128 v[244:247], v8 offset:2048
	v_xor_b32_e32 v2, 0x40, v9
	v_xor_b32_e32 v8, 0x50, v9
	ds_read_b128 v[208:211], v2 offset:4096
	ds_read_b128 v[212:215], v8 offset:4096
	s_waitcnt lgkmcnt(4)
	s_waitcnt vmcnt(15)
	v_lshlrev_b32_e32 v4, 16, v144
	v_and_b32_e32 v144, 0xffff0000, v144
	v_mul_f32_e32 v4, v232, v4
	v_mul_f32_e32 v144, v233, v144
	v_cvt_pk_bf16_f32 v4, v4, v144
	v_lshlrev_b32_e32 v5, 16, v145
	v_and_b32_e32 v145, 0xffff0000, v145
	v_mul_f32_e32 v5, v234, v5
	v_mul_f32_e32 v145, v235, v145
	v_cvt_pk_bf16_f32 v5, v5, v145
	v_lshlrev_b32_e32 v6, 16, v146
	v_and_b32_e32 v146, 0xffff0000, v146
	v_mul_f32_e32 v6, v236, v6
	v_mul_f32_e32 v146, v237, v146
	v_cvt_pk_bf16_f32 v6, v6, v146
	v_lshlrev_b32_e32 v7, 16, v147
	v_and_b32_e32 v147, 0xffff0000, v147
	v_mul_f32_e32 v7, v238, v7
	v_mul_f32_e32 v147, v239, v147
	v_cvt_pk_bf16_f32 v7, v7, v147
	global_store_dwordx4 v[10:11], v[4:7], off
	v_lshl_add_u64 v[10:11], v[10:11], 0, s[4:5]
	v_xor_b32_e32 v2, 0x60, v9
	v_xor_b32_e32 v8, 0x70, v9
	ds_read_b128 v[232:235], v2 offset:6144
	ds_read_b128 v[236:239], v8 offset:6144
	s_waitcnt lgkmcnt(4)
	s_waitcnt vmcnt(15)
	v_lshlrev_b32_e32 v12, 16, v148
	v_and_b32_e32 v148, 0xffff0000, v148
	v_mul_f32_e32 v12, v240, v12
	v_mul_f32_e32 v148, v241, v148
	v_cvt_pk_bf16_f32 v12, v12, v148
	v_lshlrev_b32_e32 v13, 16, v149
	v_and_b32_e32 v149, 0xffff0000, v149
	v_mul_f32_e32 v13, v242, v13
	v_mul_f32_e32 v149, v243, v149
	v_cvt_pk_bf16_f32 v13, v13, v149
	v_lshlrev_b32_e32 v14, 16, v150
	v_and_b32_e32 v150, 0xffff0000, v150
	v_mul_f32_e32 v14, v244, v14
	v_mul_f32_e32 v150, v245, v150
	v_cvt_pk_bf16_f32 v14, v14, v150
	v_lshlrev_b32_e32 v15, 16, v151
	v_and_b32_e32 v151, 0xffff0000, v151
	v_mul_f32_e32 v15, v246, v15
	v_mul_f32_e32 v151, v247, v151
	v_cvt_pk_bf16_f32 v15, v15, v151
	global_store_dwordx4 v[10:11], v[12:15], off
	v_lshl_add_u64 v[10:11], v[10:11], 0, s[4:5]
	v_xor_b32_e32 v8, 16, v9
	ds_read_b128 v[240:243], v9 offset:8192
	ds_read_b128 v[244:247], v8 offset:8192
	s_waitcnt lgkmcnt(4)
	s_waitcnt vmcnt(15)
	v_lshlrev_b32_e32 v4, 16, v152
	v_and_b32_e32 v152, 0xffff0000, v152
	v_mul_f32_e32 v4, v208, v4
	v_mul_f32_e32 v152, v209, v152
	v_cvt_pk_bf16_f32 v4, v4, v152
	v_lshlrev_b32_e32 v5, 16, v153
	v_and_b32_e32 v153, 0xffff0000, v153
	v_mul_f32_e32 v5, v210, v5
	v_mul_f32_e32 v153, v211, v153
	v_cvt_pk_bf16_f32 v5, v5, v153
	v_lshlrev_b32_e32 v6, 16, v154
	v_and_b32_e32 v154, 0xffff0000, v154
	v_mul_f32_e32 v6, v212, v6
	v_mul_f32_e32 v154, v213, v154
	v_cvt_pk_bf16_f32 v6, v6, v154
	v_lshlrev_b32_e32 v7, 16, v155
	v_and_b32_e32 v155, 0xffff0000, v155
	v_mul_f32_e32 v7, v214, v7
	v_mul_f32_e32 v155, v215, v155
	v_cvt_pk_bf16_f32 v7, v7, v155
	global_store_dwordx4 v[10:11], v[4:7], off
	v_lshl_add_u64 v[10:11], v[10:11], 0, s[4:5]
	v_xor_b32_e32 v2, 0x20, v9
	v_xor_b32_e32 v8, 0x30, v9
	ds_read_b128 v[208:211], v2 offset:10240
	ds_read_b128 v[212:215], v8 offset:10240
	s_waitcnt lgkmcnt(4)
	s_waitcnt vmcnt(15)
	v_lshlrev_b32_e32 v12, 16, v156
	v_and_b32_e32 v156, 0xffff0000, v156
	v_mul_f32_e32 v12, v232, v12
	v_mul_f32_e32 v156, v233, v156
	v_cvt_pk_bf16_f32 v12, v12, v156
	v_lshlrev_b32_e32 v13, 16, v157
	v_and_b32_e32 v157, 0xffff0000, v157
	v_mul_f32_e32 v13, v234, v13
	v_mul_f32_e32 v157, v235, v157
	v_cvt_pk_bf16_f32 v13, v13, v157
	v_lshlrev_b32_e32 v14, 16, v158
	v_and_b32_e32 v158, 0xffff0000, v158
	v_mul_f32_e32 v14, v236, v14
	v_mul_f32_e32 v158, v237, v158
	v_cvt_pk_bf16_f32 v14, v14, v158
	v_lshlrev_b32_e32 v15, 16, v159
	v_and_b32_e32 v159, 0xffff0000, v159
	v_mul_f32_e32 v15, v238, v15
	v_mul_f32_e32 v159, v239, v159
	v_cvt_pk_bf16_f32 v15, v15, v159
	global_store_dwordx4 v[10:11], v[12:15], off
	v_lshl_add_u64 v[10:11], v[10:11], 0, s[4:5]
	v_xor_b32_e32 v2, 0x40, v9
	v_xor_b32_e32 v8, 0x50, v9
	ds_read_b128 v[232:235], v2 offset:12288
	ds_read_b128 v[236:239], v8 offset:12288
	s_waitcnt lgkmcnt(4)
	s_waitcnt vmcnt(15)
	v_lshlrev_b32_e32 v4, 16, v160
	v_and_b32_e32 v160, 0xffff0000, v160
	v_mul_f32_e32 v4, v240, v4
	v_mul_f32_e32 v160, v241, v160
	v_cvt_pk_bf16_f32 v4, v4, v160
	v_lshlrev_b32_e32 v5, 16, v161
	v_and_b32_e32 v161, 0xffff0000, v161
	v_mul_f32_e32 v5, v242, v5
	v_mul_f32_e32 v161, v243, v161
	v_cvt_pk_bf16_f32 v5, v5, v161
	v_lshlrev_b32_e32 v6, 16, v162
	v_and_b32_e32 v162, 0xffff0000, v162
	v_mul_f32_e32 v6, v244, v6
	v_mul_f32_e32 v162, v245, v162
	v_cvt_pk_bf16_f32 v6, v6, v162
	v_lshlrev_b32_e32 v7, 16, v163
	v_and_b32_e32 v163, 0xffff0000, v163
	v_mul_f32_e32 v7, v246, v7
	v_mul_f32_e32 v163, v247, v163
	v_cvt_pk_bf16_f32 v7, v7, v163
	global_store_dwordx4 v[10:11], v[4:7], off
	v_lshl_add_u64 v[10:11], v[10:11], 0, s[4:5]
	v_xor_b32_e32 v2, 0x60, v9
	v_xor_b32_e32 v8, 0x70, v9
	ds_read_b128 v[240:243], v2 offset:14336
	ds_read_b128 v[244:247], v8 offset:14336
	s_waitcnt lgkmcnt(4)
	s_waitcnt vmcnt(15)
	v_lshlrev_b32_e32 v12, 16, v164
	v_and_b32_e32 v164, 0xffff0000, v164
	v_mul_f32_e32 v12, v208, v12
	v_mul_f32_e32 v164, v209, v164
	v_cvt_pk_bf16_f32 v12, v12, v164
	v_lshlrev_b32_e32 v13, 16, v165
	v_and_b32_e32 v165, 0xffff0000, v165
	v_mul_f32_e32 v13, v210, v13
	v_mul_f32_e32 v165, v211, v165
	v_cvt_pk_bf16_f32 v13, v13, v165
	v_lshlrev_b32_e32 v14, 16, v166
	v_and_b32_e32 v166, 0xffff0000, v166
	v_mul_f32_e32 v14, v212, v14
	v_mul_f32_e32 v166, v213, v166
	v_cvt_pk_bf16_f32 v14, v14, v166
	v_lshlrev_b32_e32 v15, 16, v167
	v_and_b32_e32 v167, 0xffff0000, v167
	v_mul_f32_e32 v15, v214, v15
	v_mul_f32_e32 v167, v215, v167
	v_cvt_pk_bf16_f32 v15, v15, v167
	global_store_dwordx4 v[10:11], v[12:15], off
	v_lshl_add_u64 v[10:11], v[10:11], 0, s[4:5]
	v_xor_b32_e32 v8, 16, v9
	ds_read_b128 v[208:211], v9 offset:16384
	ds_read_b128 v[212:215], v8 offset:16384
	s_waitcnt lgkmcnt(4)
	s_waitcnt vmcnt(15)
	v_lshlrev_b32_e32 v4, 16, v168
	v_and_b32_e32 v168, 0xffff0000, v168
	v_mul_f32_e32 v4, v232, v4
	v_mul_f32_e32 v168, v233, v168
	v_cvt_pk_bf16_f32 v4, v4, v168
	v_lshlrev_b32_e32 v5, 16, v169
	v_and_b32_e32 v169, 0xffff0000, v169
	v_mul_f32_e32 v5, v234, v5
	v_mul_f32_e32 v169, v235, v169
	v_cvt_pk_bf16_f32 v5, v5, v169
	v_lshlrev_b32_e32 v6, 16, v170
	v_and_b32_e32 v170, 0xffff0000, v170
	v_mul_f32_e32 v6, v236, v6
	v_mul_f32_e32 v170, v237, v170
	v_cvt_pk_bf16_f32 v6, v6, v170
	v_lshlrev_b32_e32 v7, 16, v171
	v_and_b32_e32 v171, 0xffff0000, v171
	v_mul_f32_e32 v7, v238, v7
	v_mul_f32_e32 v171, v239, v171
	v_cvt_pk_bf16_f32 v7, v7, v171
	global_store_dwordx4 v[10:11], v[4:7], off
	v_lshl_add_u64 v[10:11], v[10:11], 0, s[4:5]
	v_xor_b32_e32 v2, 0x20, v9
	v_xor_b32_e32 v8, 0x30, v9
	ds_read_b128 v[232:235], v2 offset:18432
	ds_read_b128 v[236:239], v8 offset:18432
	s_waitcnt lgkmcnt(4)
	s_waitcnt vmcnt(15)
	v_lshlrev_b32_e32 v12, 16, v172
	v_and_b32_e32 v172, 0xffff0000, v172
	v_mul_f32_e32 v12, v240, v12
	v_mul_f32_e32 v172, v241, v172
	v_cvt_pk_bf16_f32 v12, v12, v172
	v_lshlrev_b32_e32 v13, 16, v173
	v_and_b32_e32 v173, 0xffff0000, v173
	v_mul_f32_e32 v13, v242, v13
	v_mul_f32_e32 v173, v243, v173
	v_cvt_pk_bf16_f32 v13, v13, v173
	v_lshlrev_b32_e32 v14, 16, v174
	v_and_b32_e32 v174, 0xffff0000, v174
	v_mul_f32_e32 v14, v244, v14
	v_mul_f32_e32 v174, v245, v174
	v_cvt_pk_bf16_f32 v14, v14, v174
	v_lshlrev_b32_e32 v15, 16, v175
	v_and_b32_e32 v175, 0xffff0000, v175
	v_mul_f32_e32 v15, v246, v15
	v_mul_f32_e32 v175, v247, v175
	v_cvt_pk_bf16_f32 v15, v15, v175
	global_store_dwordx4 v[10:11], v[12:15], off
	v_lshl_add_u64 v[10:11], v[10:11], 0, s[4:5]
	v_xor_b32_e32 v2, 0x40, v9
	v_xor_b32_e32 v8, 0x50, v9
	ds_read_b128 v[240:243], v2 offset:20480
	ds_read_b128 v[244:247], v8 offset:20480
	s_waitcnt lgkmcnt(4)
	s_waitcnt vmcnt(15)
	v_lshlrev_b32_e32 v4, 16, v176
	v_and_b32_e32 v176, 0xffff0000, v176
	v_mul_f32_e32 v4, v208, v4
	v_mul_f32_e32 v176, v209, v176
	v_cvt_pk_bf16_f32 v4, v4, v176
	v_lshlrev_b32_e32 v5, 16, v177
	v_and_b32_e32 v177, 0xffff0000, v177
	v_mul_f32_e32 v5, v210, v5
	v_mul_f32_e32 v177, v211, v177
	v_cvt_pk_bf16_f32 v5, v5, v177
	v_lshlrev_b32_e32 v6, 16, v178
	v_and_b32_e32 v178, 0xffff0000, v178
	v_mul_f32_e32 v6, v212, v6
	v_mul_f32_e32 v178, v213, v178
	v_cvt_pk_bf16_f32 v6, v6, v178
	v_lshlrev_b32_e32 v7, 16, v179
	v_and_b32_e32 v179, 0xffff0000, v179
	v_mul_f32_e32 v7, v214, v7
	v_mul_f32_e32 v179, v215, v179
	v_cvt_pk_bf16_f32 v7, v7, v179
	global_store_dwordx4 v[10:11], v[4:7], off
	v_lshl_add_u64 v[10:11], v[10:11], 0, s[4:5]
	v_xor_b32_e32 v2, 0x60, v9
	v_xor_b32_e32 v8, 0x70, v9
	ds_read_b128 v[208:211], v2 offset:22528
	ds_read_b128 v[212:215], v8 offset:22528
	s_waitcnt lgkmcnt(4)
	s_waitcnt vmcnt(15)
	v_lshlrev_b32_e32 v12, 16, v180
	v_and_b32_e32 v180, 0xffff0000, v180
	v_mul_f32_e32 v12, v232, v12
	v_mul_f32_e32 v180, v233, v180
	v_cvt_pk_bf16_f32 v12, v12, v180
	v_lshlrev_b32_e32 v13, 16, v181
	v_and_b32_e32 v181, 0xffff0000, v181
	v_mul_f32_e32 v13, v234, v13
	v_mul_f32_e32 v181, v235, v181
	v_cvt_pk_bf16_f32 v13, v13, v181
	v_lshlrev_b32_e32 v14, 16, v182
	v_and_b32_e32 v182, 0xffff0000, v182
	v_mul_f32_e32 v14, v236, v14
	v_mul_f32_e32 v182, v237, v182
	v_cvt_pk_bf16_f32 v14, v14, v182
	v_lshlrev_b32_e32 v15, 16, v183
	v_and_b32_e32 v183, 0xffff0000, v183
	v_mul_f32_e32 v15, v238, v15
	v_mul_f32_e32 v183, v239, v183
	v_cvt_pk_bf16_f32 v15, v15, v183
	global_store_dwordx4 v[10:11], v[12:15], off
	v_lshl_add_u64 v[10:11], v[10:11], 0, s[4:5]
	v_xor_b32_e32 v8, 16, v9
	ds_read_b128 v[232:235], v9 offset:24576
	ds_read_b128 v[236:239], v8 offset:24576
	s_waitcnt lgkmcnt(4)
	s_waitcnt vmcnt(15)
	v_lshlrev_b32_e32 v4, 16, v184
	v_and_b32_e32 v184, 0xffff0000, v184
	v_mul_f32_e32 v4, v240, v4
	v_mul_f32_e32 v184, v241, v184
	v_cvt_pk_bf16_f32 v4, v4, v184
	v_lshlrev_b32_e32 v5, 16, v185
	v_and_b32_e32 v185, 0xffff0000, v185
	v_mul_f32_e32 v5, v242, v5
	v_mul_f32_e32 v185, v243, v185
	v_cvt_pk_bf16_f32 v5, v5, v185
	v_lshlrev_b32_e32 v6, 16, v186
	v_and_b32_e32 v186, 0xffff0000, v186
	v_mul_f32_e32 v6, v244, v6
	v_mul_f32_e32 v186, v245, v186
	v_cvt_pk_bf16_f32 v6, v6, v186
	v_lshlrev_b32_e32 v7, 16, v187
	v_and_b32_e32 v187, 0xffff0000, v187
	v_mul_f32_e32 v7, v246, v7
	v_mul_f32_e32 v187, v247, v187
	v_cvt_pk_bf16_f32 v7, v7, v187
	global_store_dwordx4 v[10:11], v[4:7], off
	v_lshl_add_u64 v[10:11], v[10:11], 0, s[4:5]
	v_xor_b32_e32 v2, 0x20, v9
	v_xor_b32_e32 v8, 0x30, v9
	ds_read_b128 v[240:243], v2 offset:26624
	ds_read_b128 v[244:247], v8 offset:26624
	s_waitcnt lgkmcnt(4)
	s_waitcnt vmcnt(15)
	v_lshlrev_b32_e32 v12, 16, v188
	v_and_b32_e32 v188, 0xffff0000, v188
	v_mul_f32_e32 v12, v208, v12
	v_mul_f32_e32 v188, v209, v188
	v_cvt_pk_bf16_f32 v12, v12, v188
	v_lshlrev_b32_e32 v13, 16, v189
	v_and_b32_e32 v189, 0xffff0000, v189
	v_mul_f32_e32 v13, v210, v13
	v_mul_f32_e32 v189, v211, v189
	v_cvt_pk_bf16_f32 v13, v13, v189
	v_lshlrev_b32_e32 v14, 16, v190
	v_and_b32_e32 v190, 0xffff0000, v190
	v_mul_f32_e32 v14, v212, v14
	v_mul_f32_e32 v190, v213, v190
	v_cvt_pk_bf16_f32 v14, v14, v190
	v_lshlrev_b32_e32 v15, 16, v191
	v_and_b32_e32 v191, 0xffff0000, v191
	v_mul_f32_e32 v15, v214, v15
	v_mul_f32_e32 v191, v215, v191
	v_cvt_pk_bf16_f32 v15, v15, v191
	global_store_dwordx4 v[10:11], v[12:15], off
	v_lshl_add_u64 v[10:11], v[10:11], 0, s[4:5]
	v_xor_b32_e32 v2, 0x40, v9
	v_xor_b32_e32 v8, 0x50, v9
	ds_read_b128 v[208:211], v2 offset:28672
	ds_read_b128 v[212:215], v8 offset:28672
	s_waitcnt lgkmcnt(4)
	s_waitcnt vmcnt(15)
	v_lshlrev_b32_e32 v4, 16, v216
	v_and_b32_e32 v216, 0xffff0000, v216
	v_mul_f32_e32 v4, v232, v4
	v_mul_f32_e32 v216, v233, v216
	v_cvt_pk_bf16_f32 v4, v4, v216
	v_lshlrev_b32_e32 v5, 16, v217
	v_and_b32_e32 v217, 0xffff0000, v217
	v_mul_f32_e32 v5, v234, v5
	v_mul_f32_e32 v217, v235, v217
	v_cvt_pk_bf16_f32 v5, v5, v217
	v_lshlrev_b32_e32 v6, 16, v218
	v_and_b32_e32 v218, 0xffff0000, v218
	v_mul_f32_e32 v6, v236, v6
	v_mul_f32_e32 v218, v237, v218
	v_cvt_pk_bf16_f32 v6, v6, v218
	v_lshlrev_b32_e32 v7, 16, v219
	v_and_b32_e32 v219, 0xffff0000, v219
	v_mul_f32_e32 v7, v238, v7
	v_mul_f32_e32 v219, v239, v219
	v_cvt_pk_bf16_f32 v7, v7, v219
	global_store_dwordx4 v[10:11], v[4:7], off
	v_lshl_add_u64 v[10:11], v[10:11], 0, s[4:5]
	v_xor_b32_e32 v2, 0x60, v9
	v_xor_b32_e32 v8, 0x70, v9
	ds_read_b128 v[232:235], v2 offset:30720
	ds_read_b128 v[236:239], v8 offset:30720
	s_waitcnt lgkmcnt(4)
	s_waitcnt vmcnt(15)
	v_lshlrev_b32_e32 v12, 16, v220
	v_and_b32_e32 v220, 0xffff0000, v220
	v_mul_f32_e32 v12, v240, v12
	v_mul_f32_e32 v220, v241, v220
	v_cvt_pk_bf16_f32 v12, v12, v220
	v_lshlrev_b32_e32 v13, 16, v221
	v_and_b32_e32 v221, 0xffff0000, v221
	v_mul_f32_e32 v13, v242, v13
	v_mul_f32_e32 v221, v243, v221
	v_cvt_pk_bf16_f32 v13, v13, v221
	v_lshlrev_b32_e32 v14, 16, v222
	v_and_b32_e32 v222, 0xffff0000, v222
	v_mul_f32_e32 v14, v244, v14
	v_mul_f32_e32 v222, v245, v222
	v_cvt_pk_bf16_f32 v14, v14, v222
	v_lshlrev_b32_e32 v15, 16, v223
	v_and_b32_e32 v223, 0xffff0000, v223
	v_mul_f32_e32 v15, v246, v15
	v_mul_f32_e32 v223, v247, v223
	v_cvt_pk_bf16_f32 v15, v15, v223
	global_store_dwordx4 v[10:11], v[12:15], off
	v_lshl_add_u64 v[10:11], v[10:11], 0, s[4:5]
	s_waitcnt lgkmcnt(2)
	s_waitcnt vmcnt(15)
	v_lshlrev_b32_e32 v4, 16, v224
	v_and_b32_e32 v224, 0xffff0000, v224
	v_mul_f32_e32 v4, v208, v4
	v_mul_f32_e32 v224, v209, v224
	v_cvt_pk_bf16_f32 v4, v4, v224
	v_lshlrev_b32_e32 v5, 16, v225
	v_and_b32_e32 v225, 0xffff0000, v225
	v_mul_f32_e32 v5, v210, v5
	v_mul_f32_e32 v225, v211, v225
	v_cvt_pk_bf16_f32 v5, v5, v225
	v_lshlrev_b32_e32 v6, 16, v226
	v_and_b32_e32 v226, 0xffff0000, v226
	v_mul_f32_e32 v6, v212, v6
	v_mul_f32_e32 v226, v213, v226
	v_cvt_pk_bf16_f32 v6, v6, v226
	v_lshlrev_b32_e32 v7, 16, v227
	v_and_b32_e32 v227, 0xffff0000, v227
	v_mul_f32_e32 v7, v214, v7
	v_mul_f32_e32 v227, v215, v227
	v_cvt_pk_bf16_f32 v7, v7, v227
	global_store_dwordx4 v[10:11], v[4:7], off
	v_lshl_add_u64 v[10:11], v[10:11], 0, s[4:5]
	s_waitcnt lgkmcnt(0)
	s_waitcnt vmcnt(15)
	v_lshlrev_b32_e32 v12, 16, v228
	v_and_b32_e32 v228, 0xffff0000, v228
	v_mul_f32_e32 v12, v232, v12
	v_mul_f32_e32 v228, v233, v228
	v_cvt_pk_bf16_f32 v12, v12, v228
	v_lshlrev_b32_e32 v13, 16, v229
	v_and_b32_e32 v229, 0xffff0000, v229
	v_mul_f32_e32 v13, v234, v13
	v_mul_f32_e32 v229, v235, v229
	v_cvt_pk_bf16_f32 v13, v13, v229
	v_lshlrev_b32_e32 v14, 16, v230
	v_and_b32_e32 v230, 0xffff0000, v230
	v_mul_f32_e32 v14, v236, v14
	v_mul_f32_e32 v230, v237, v230
	v_cvt_pk_bf16_f32 v14, v14, v230
	v_lshlrev_b32_e32 v15, 16, v231
	v_and_b32_e32 v231, 0xffff0000, v231
	v_mul_f32_e32 v15, v238, v15
	v_mul_f32_e32 v231, v239, v231
	v_cvt_pk_bf16_f32 v15, v15, v231
	global_store_dwordx4 v[10:11], v[12:15], off
	s_branch .LBB0_306
